# conv: next item's first 10 rows prefetched during the last 8 tokens of the current item (cross-item prefetch)
# speedup vs baseline: 1.0020x; 1.0020x over previous
; __device__ __forceinline__ uint4 ld_nt16(const void* p) { const u32x4_t t = __builtin_nontemporal_load((const u32x4_t*)p); return make_uint4(t[0], t[1], t[2], t[3]); }
; __device__ void conv_phase(int swave, const Params& p, int layer, int h) {
;     ...
;   for (int it = bidx * 512 + tidx; it < (TOK / 16) * NG; it += gridDim.x * 512) {
;     const int f8 = (it % NG) * 8, t0 = (it / NG) * 16, s0 = t0 & (SEQ - 1);
;     const int fa = FC0 + f8, fv = FFN + FC0 + f8;
;     float wa[3][8], wv[3][8], ba[8], bv[8];
; #pragma unroll
;     for (int tap = 0; tap < 3; ++tap) {
;       const float4 a0 = *(const float4*)(cw + tap * 5632 + fa), a1 = *(const float4*)(cw + tap * 5632 + fa + 4);
;       const float4 v0 = *(const float4*)(cw + tap * 5632 + fv), v1 = *(const float4*)(cw + tap * 5632 + fv + 4);
;       wa[tap][0] = a0.x; wa[tap][1] = a0.y; wa[tap][2] = a0.z; wa[tap][3] = a0.w; wa[tap][4] = a1.x; wa[tap][5] = a1.y; wa[tap][6] = a1.z; wa[tap][7] = a1.w;
;       wv[tap][0] = v0.x; wv[tap][1] = v0.y; wv[tap][2] = v0.z; wv[tap][3] = v0.w; wv[tap][4] = v1.x; wv[tap][5] = v1.y; wv[tap][6] = v1.z; wv[tap][7] = v1.w;
;     }
;     {
;       const float4 a0 = *(const float4*)(cb + fa), a1 = *(const float4*)(cb + fa + 4), v0 = *(const float4*)(cb + fv), v1 = *(const float4*)(cb + fv + 4);
;       ba[0] = a0.x; ba[1] = a0.y; ba[2] = a0.z; ba[3] = a0.w; ba[4] = a1.x; ba[5] = a1.y; ba[6] = a1.z; ba[7] = a1.w;
;       bv[0] = v0.x; bv[1] = v0.y; bv[2] = v0.z; bv[3] = v0.w; bv[4] = v1.x; bv[5] = v1.y; bv[6] = v1.z; bv[7] = v1.w;
;     }
;     const bf16_t* base = U + (size_t)t0 * ULD + f8;
;     const uint4 zero4 = make_uint4(0u, 0u, 0u, 0u);
;     uint4 pa = zero4, pv = zero4;
;     if (s0 > 0) { pa = ld_nt16(base - ULD); pv = ld_nt16(base - ULD + FFNH); }
;     uint4 ca = ld_nt16(base), cv = ld_nt16(base + FFNH);
; #pragma unroll 4
;     for (int i = 0; i < 16; ++i) {
;       uint4 na = zero4, nv = zero4;
;       if (s0 + i + 1 < SEQ) { na = ld_nt16(base + (size_t)(i + 1) * ULD); nv = ld_nt16(base + (size_t)(i + 1) * ULD + FFNH); }
.LBB0_707:
	v_add_u32_e32 v135, s57, v135
	v_cmp_le_i32_e32 vcc, s44, v135
	s_or_b64 s[12:13], vcc, s[12:13]
	s_andn2_b64 exec, exec, s[12:13]
	s_cbranch_execz .LBB0_715
	s_branch .Lconv_short
.LBB0_708:
	v_mul_hi_u32 v0, v135, v142
	v_mul_lo_u32 v1, v0, s45
	v_sub_u32_e32 v1, v135, v1
	v_add_u32_e32 v2, 1, v0
	v_cmp_le_u32_e32 vcc, s45, v1
	s_lshl_b32 s24, s10, 5
	s_lshl_b32 s25, s10, 4
	v_cndmask_b32_e32 v0, v0, v2, vcc
	v_subrev_u32_e32 v2, s45, v1
	v_cndmask_b32_e32 v1, v1, v2, vcc
	v_add_u32_e32 v2, 1, v0
	v_cmp_le_u32_e32 vcc, s45, v1
	s_nop 1
	v_cndmask_b32_e32 v0, v0, v2, vcc
	v_mul_lo_u32 v1, v0, s45
	v_sub_u32_e32 v1, v135, v1
	v_lshlrev_b32_e32 v1, 3, v1
	v_add_u32_e32 v2, s35, v1
	v_lshlrev_b32_e32 v68, 2, v2
	v_add_u32_e32 v69, 0x2c00, v68
	global_load_dwordx4 v[4:7], v68, s[6:7] offset:16
	global_load_dwordx4 v[8:11], v68, s[6:7]
	global_load_dwordx4 v[12:15], v69, s[6:7] offset:16
	global_load_dwordx4 v[16:19], v69, s[6:7]
	global_load_dwordx4 v[20:23], v68, s[16:17] offset:16
	global_load_dwordx4 v[24:27], v68, s[16:17]
	global_load_dwordx4 v[28:31], v69, s[16:17] offset:16
	global_load_dwordx4 v[32:35], v69, s[16:17]
	global_load_dwordx4 v[36:39], v68, s[18:19] offset:16
	global_load_dwordx4 v[40:43], v68, s[18:19]
	global_load_dwordx4 v[44:47], v69, s[18:19] offset:16
	global_load_dwordx4 v[48:51], v69, s[18:19]
	global_load_dwordx4 v[52:55], v68, s[8:9] offset:16
	global_load_dwordx4 v[56:59], v68, s[8:9]
	global_load_dwordx4 v[60:63], v69, s[8:9] offset:16
	global_load_dwordx4 v[64:67], v69, s[8:9]
	v_lshlrev_b32_e32 v1, 1, v1
	v_mul_lo_u32 v2, v0, s24
	v_add_u32_e32 v2, v2, v1
	v_lshl_add_u64 v[68:69], s[4:5], 0, v[2:3]
	v_mul_lo_u32 v2, v0, s25
	v_add_u32_e32 v2, v2, v1
	v_lshl_add_u64 v[70:71], s[40:41], 0, v[2:3]
	v_lshl_add_u64 v[72:73], s[14:15], 1, v[68:69]
	v_and_b32_e32 v0, 0x7f, v0
	v_cmp_ne_u32_e64 s[2:3], 0, v0
	v_mov_b32_e32 v2, 0x7f
	v_cmp_ne_u32_e64 s[20:21], v0, v2
	global_load_dwordx4 v[160:163], v[72:73], off nt
	v_lshl_add_u64 v[72:73], v[72:73], 0, s[10:11]
	global_load_dwordx4 v[164:167], v[72:73], off nt
	v_lshl_add_u64 v[72:73], v[72:73], 0, s[10:11]
	global_load_dwordx4 v[168:171], v[72:73], off nt
	v_lshl_add_u64 v[72:73], v[72:73], 0, s[10:11]
	global_load_dwordx4 v[172:175], v[72:73], off nt
	v_lshl_add_u64 v[72:73], v[72:73], 0, s[10:11]
	global_load_dwordx4 v[176:179], v[72:73], off nt
	v_lshl_add_u64 v[72:73], v[72:73], 0, s[10:11]
	global_load_dwordx4 v[180:183], v[72:73], off nt
	v_lshl_add_u64 v[72:73], v[72:73], 0, s[10:11]
	global_load_dwordx4 v[184:187], v[72:73], off nt
	v_lshl_add_u64 v[72:73], v[72:73], 0, s[10:11]
	global_load_dwordx4 v[188:191], v[72:73], off nt
	v_lshl_add_u64 v[72:73], v[72:73], 0, s[10:11]
	global_load_dwordx4 v[192:195], v[72:73], off nt
	v_lshl_add_u64 v[72:73], v[72:73], 0, s[10:11]
	global_load_dwordx4 v[196:199], v[72:73], off nt
	v_lshl_add_u64 v[72:73], v[72:73], 0, s[10:11]
	global_load_dwordx4 v[200:203], v[72:73], off nt
	v_lshl_add_u64 v[72:73], v[72:73], 0, s[10:11]
	global_load_dwordx4 v[204:207], v[72:73], off nt
	v_lshl_add_u64 v[72:73], v[72:73], 0, s[10:11]
	global_load_dwordx4 v[208:211], v[72:73], off nt
	v_lshl_add_u64 v[72:73], v[72:73], 0, s[10:11]
	global_load_dwordx4 v[212:215], v[72:73], off nt
	v_lshl_add_u64 v[72:73], v[72:73], 0, s[10:11]
	global_load_dwordx4 v[216:219], v[72:73], off nt
	v_lshl_add_u64 v[72:73], v[72:73], 0, s[10:11]
	global_load_dwordx4 v[220:223], v[72:73], off nt
	v_lshl_add_u64 v[72:73], v[72:73], 0, s[10:11]
	global_load_dwordx4 v[224:227], v[72:73], off nt
	v_lshl_add_u64 v[72:73], v[72:73], 0, s[10:11]
	global_load_dwordx4 v[228:231], v[72:73], off nt
	v_lshl_add_u64 v[72:73], v[72:73], 0, s[10:11]
	global_load_dwordx4 v[232:235], v[72:73], off nt
	v_lshl_add_u64 v[72:73], v[72:73], 0, s[10:11]
	global_load_dwordx4 v[236:239], v[72:73], off nt
	v_lshl_add_u64 v[72:73], v[72:73], 0, s[10:11]
	s_branch .Lconv_common
.Lconv_short:
	v_mul_hi_u32 v0, v135, v142
	v_mul_lo_u32 v1, v0, s45
	v_sub_u32_e32 v1, v135, v1
	v_add_u32_e32 v2, 1, v0
	v_cmp_le_u32_e32 vcc, s45, v1
	s_lshl_b32 s24, s10, 5
	s_lshl_b32 s25, s10, 4
	v_cndmask_b32_e32 v0, v0, v2, vcc
	v_subrev_u32_e32 v2, s45, v1
	v_cndmask_b32_e32 v1, v1, v2, vcc
	v_add_u32_e32 v2, 1, v0
	v_cmp_le_u32_e32 vcc, s45, v1
	s_nop 1
	v_cndmask_b32_e32 v0, v0, v2, vcc
	v_mul_lo_u32 v1, v0, s45
	v_sub_u32_e32 v1, v135, v1
	v_lshlrev_b32_e32 v1, 3, v1
	v_add_u32_e32 v2, s35, v1
	v_lshlrev_b32_e32 v68, 2, v2
	v_add_u32_e32 v69, 0x2c00, v68
	global_load_dwordx4 v[4:7], v68, s[6:7] offset:16
	global_load_dwordx4 v[8:11], v68, s[6:7]
	global_load_dwordx4 v[12:15], v69, s[6:7] offset:16
	global_load_dwordx4 v[16:19], v69, s[6:7]
	global_load_dwordx4 v[20:23], v68, s[16:17] offset:16
	global_load_dwordx4 v[24:27], v68, s[16:17]
	global_load_dwordx4 v[28:31], v69, s[16:17] offset:16
	global_load_dwordx4 v[32:35], v69, s[16:17]
	global_load_dwordx4 v[36:39], v68, s[18:19] offset:16
	global_load_dwordx4 v[40:43], v68, s[18:19]
	global_load_dwordx4 v[44:47], v69, s[18:19] offset:16
	global_load_dwordx4 v[48:51], v69, s[18:19]
	global_load_dwordx4 v[52:55], v68, s[8:9] offset:16
	global_load_dwordx4 v[56:59], v68, s[8:9]
	global_load_dwordx4 v[60:63], v69, s[8:9] offset:16
	global_load_dwordx4 v[64:67], v69, s[8:9]
	v_lshlrev_b32_e32 v1, 1, v1
	v_mul_lo_u32 v2, v0, s25
	v_add_u32_e32 v2, v2, v1
	v_lshl_add_u64 v[70:71], s[40:41], 0, v[2:3]
	v_and_b32_e32 v0, 0x7f, v0
	v_cmp_ne_u32_e64 s[2:3], 0, v0
	v_mov_b32_e32 v2, 0x7f
	v_cmp_ne_u32_e64 s[20:21], v0, v2
; __device__ __forceinline__ uint4 ld_nt16(const void* p) { const u32x4_t t = __builtin_nontemporal_load((const u32x4_t*)p); return make_uint4(t[0], t[1], t[2], t[3]); }
; __device__ __forceinline__ float lo_bf(unsigned u) { return __uint_as_float(u << 16); }
; __device__ __forceinline__ float hi_bf(unsigned u) { return __uint_as_float(u & 0xffff0000u); }
; __device__ void conv_phase(int swave, const Params& p, int layer, int h) {
;     ...
;     if (s0 > 0) { pa = ld_nt16(base - ULD); pv = ld_nt16(base - ULD + FFNH); }
;     uint4 ca = ld_nt16(base), cv = ld_nt16(base + FFNH);
; #pragma unroll 4
;     for (int i = 0; i < 16; ++i) {
;       uint4 na = zero4, nv = zero4;
;       if (s0 + i + 1 < SEQ) { na = ld_nt16(base + (size_t)(i + 1) * ULD); nv = ld_nt16(base + (size_t)(i + 1) * ULD + FFNH); }
;       const unsigned rp[4] = {pa.x, pa.y, pa.z, pa.w}, rc[4] = {ca.x, ca.y, ca.z, ca.w}, rn[4] = {na.x, na.y, na.z, na.w};
;       const unsigned qp[4] = {pv.x, pv.y, pv.z, pv.w}, qc[4] = {cv.x, cv.y, cv.z, cv.w}, qn[4] = {nv.x, nv.y, nv.z, nv.w};
;       float oa[8], ov[8];
; #pragma unroll
;       for (int e = 0; e < 4; ++e) {
;         oa[2 * e] = ba[2 * e] + lo_bf(rp[e]) * wa[0][2 * e] + lo_bf(rc[e]) * wa[1][2 * e] + lo_bf(rn[e]) * wa[2][2 * e];
;         oa[2 * e + 1] = ba[2 * e + 1] + hi_bf(rp[e]) * wa[0][2 * e + 1] + hi_bf(rc[e]) * wa[1][2 * e + 1] + hi_bf(rn[e]) * wa[2][2 * e + 1];
;         ov[2 * e] = bv[2 * e] + lo_bf(qp[e]) * wv[0][2 * e] + lo_bf(qc[e]) * wv[1][2 * e] + lo_bf(qn[e]) * wv[2][2 * e];
;         ov[2 * e + 1] = bv[2 * e + 1] + hi_bf(qp[e]) * wv[0][2 * e + 1] + hi_bf(qc[e]) * wv[1][2 * e + 1] + hi_bf(qn[e]) * wv[2][2 * e + 1];
;       }
.Lconv_common:
	s_waitcnt vmcnt(0)
	v_cndmask_b32_e64 v160, 0, v160, s[2:3]
	v_cndmask_b32_e64 v161, 0, v161, s[2:3]
	v_cndmask_b32_e64 v162, 0, v162, s[2:3]
	v_cndmask_b32_e64 v163, 0, v163, s[2:3]
	v_cndmask_b32_e64 v164, 0, v164, s[2:3]
	v_cndmask_b32_e64 v165, 0, v165, s[2:3]
	v_cndmask_b32_e64 v166, 0, v166, s[2:3]
	v_cndmask_b32_e64 v167, 0, v167, s[2:3]
	v_lshlrev_b32_e32 v126, 16, v160
	v_and_b32_e32 v127, 0xffff0000, v160
	v_pk_fma_f32 v[74:75], v[8:9], v[126:127], v[56:57]
	v_lshlrev_b32_e32 v128, 16, v161
	v_and_b32_e32 v129, 0xffff0000, v161
	v_pk_fma_f32 v[76:77], v[10:11], v[128:129], v[58:59]
	v_lshlrev_b32_e32 v126, 16, v162
	v_and_b32_e32 v127, 0xffff0000, v162
	v_pk_fma_f32 v[78:79], v[4:5], v[126:127], v[52:53]
	v_lshlrev_b32_e32 v128, 16, v163
	v_and_b32_e32 v129, 0xffff0000, v163
	v_pk_fma_f32 v[80:81], v[6:7], v[128:129], v[54:55]
	v_lshlrev_b32_e32 v126, 16, v164
	v_and_b32_e32 v127, 0xffff0000, v164
	v_pk_fma_f32 v[82:83], v[16:17], v[126:127], v[64:65]
	v_lshlrev_b32_e32 v128, 16, v165
	v_and_b32_e32 v129, 0xffff0000, v165
	v_pk_fma_f32 v[84:85], v[18:19], v[128:129], v[66:67]
	v_lshlrev_b32_e32 v126, 16, v166
	v_and_b32_e32 v127, 0xffff0000, v166
	v_pk_fma_f32 v[86:87], v[12:13], v[126:127], v[60:61]
	v_lshlrev_b32_e32 v128, 16, v167
	v_and_b32_e32 v129, 0xffff0000, v167
	v_pk_fma_f32 v[88:89], v[14:15], v[128:129], v[62:63]
	global_load_dwordx4 v[160:163], v[72:73], off nt
	v_lshl_add_u64 v[72:73], v[72:73], 0, s[10:11]
	global_load_dwordx4 v[164:167], v[72:73], off nt
	v_lshl_add_u64 v[72:73], v[72:73], 0, s[10:11]
	v_lshlrev_b32_e32 v126, 16, v168
	v_and_b32_e32 v127, 0xffff0000, v168
	v_pk_fma_f32 v[90:91], v[8:9], v[126:127], v[56:57]
	v_pk_fma_f32 v[74:75], v[24:25], v[126:127], v[74:75]
	v_lshlrev_b32_e32 v128, 16, v169
	v_and_b32_e32 v129, 0xffff0000, v169
	v_pk_fma_f32 v[92:93], v[10:11], v[128:129], v[58:59]
	v_pk_fma_f32 v[76:77], v[26:27], v[128:129], v[76:77]
	v_lshlrev_b32_e32 v126, 16, v170
	v_and_b32_e32 v127, 0xffff0000, v170
	v_pk_fma_f32 v[94:95], v[4:5], v[126:127], v[52:53]
	v_pk_fma_f32 v[78:79], v[20:21], v[126:127], v[78:79]
	v_lshlrev_b32_e32 v128, 16, v171
	v_and_b32_e32 v129, 0xffff0000, v171
	v_pk_fma_f32 v[96:97], v[6:7], v[128:129], v[54:55]
	v_pk_fma_f32 v[80:81], v[22:23], v[128:129], v[80:81]
	v_lshlrev_b32_e32 v126, 16, v172
	v_and_b32_e32 v127, 0xffff0000, v172
	v_pk_fma_f32 v[98:99], v[16:17], v[126:127], v[64:65]
	v_pk_fma_f32 v[82:83], v[32:33], v[126:127], v[82:83]
	v_lshlrev_b32_e32 v128, 16, v173
	v_and_b32_e32 v129, 0xffff0000, v173
	v_pk_fma_f32 v[100:101], v[18:19], v[128:129], v[66:67]
	v_pk_fma_f32 v[84:85], v[34:35], v[128:129], v[84:85]
	v_lshlrev_b32_e32 v126, 16, v174
	v_and_b32_e32 v127, 0xffff0000, v174
	v_pk_fma_f32 v[102:103], v[12:13], v[126:127], v[60:61]
	v_pk_fma_f32 v[86:87], v[28:29], v[126:127], v[86:87]
	v_lshlrev_b32_e32 v128, 16, v175
	v_and_b32_e32 v129, 0xffff0000, v175
	v_pk_fma_f32 v[104:105], v[14:15], v[128:129], v[62:63]
	v_pk_fma_f32 v[88:89], v[30:31], v[128:129], v[88:89]
	global_load_dwordx4 v[168:171], v[72:73], off nt
	v_lshl_add_u64 v[72:73], v[72:73], 0, s[10:11]
	global_load_dwordx4 v[172:175], v[72:73], off nt
	v_lshl_add_u64 v[72:73], v[72:73], 0, s[10:11]
	v_lshlrev_b32_e32 v126, 16, v176
	v_and_b32_e32 v127, 0xffff0000, v176
	v_pk_fma_f32 v[106:107], v[8:9], v[126:127], v[56:57]
	v_pk_fma_f32 v[90:91], v[24:25], v[126:127], v[90:91]
	v_pk_fma_f32 v[74:75], v[40:41], v[126:127], v[74:75]
	v_lshlrev_b32_e32 v128, 16, v177
	v_and_b32_e32 v129, 0xffff0000, v177
	v_pk_fma_f32 v[108:109], v[10:11], v[128:129], v[58:59]
	v_pk_fma_f32 v[92:93], v[26:27], v[128:129], v[92:93]
	v_pk_fma_f32 v[76:77], v[42:43], v[128:129], v[76:77]
	v_lshlrev_b32_e32 v126, 16, v178
	v_and_b32_e32 v127, 0xffff0000, v178
	v_pk_fma_f32 v[110:111], v[4:5], v[126:127], v[52:53]
	v_pk_fma_f32 v[94:95], v[20:21], v[126:127], v[94:95]
	v_pk_fma_f32 v[78:79], v[36:37], v[126:127], v[78:79]
	v_lshlrev_b32_e32 v128, 16, v179
	v_and_b32_e32 v129, 0xffff0000, v179
	v_pk_fma_f32 v[112:113], v[6:7], v[128:129], v[54:55]
	v_pk_fma_f32 v[96:97], v[22:23], v[128:129], v[96:97]
	v_pk_fma_f32 v[80:81], v[38:39], v[128:129], v[80:81]
	v_lshlrev_b32_e32 v126, 16, v180
	v_and_b32_e32 v127, 0xffff0000, v180
	v_pk_fma_f32 v[114:115], v[16:17], v[126:127], v[64:65]
	v_pk_fma_f32 v[98:99], v[32:33], v[126:127], v[98:99]
	v_pk_fma_f32 v[82:83], v[48:49], v[126:127], v[82:83]
	v_lshlrev_b32_e32 v128, 16, v181
	v_and_b32_e32 v129, 0xffff0000, v181
	v_pk_fma_f32 v[116:117], v[18:19], v[128:129], v[66:67]
	v_pk_fma_f32 v[100:101], v[34:35], v[128:129], v[100:101]
	v_pk_fma_f32 v[84:85], v[50:51], v[128:129], v[84:85]
	v_lshlrev_b32_e32 v126, 16, v182
	v_and_b32_e32 v127, 0xffff0000, v182
	v_pk_fma_f32 v[118:119], v[12:13], v[126:127], v[60:61]
	v_pk_fma_f32 v[102:103], v[28:29], v[126:127], v[102:103]
	v_pk_fma_f32 v[86:87], v[44:45], v[126:127], v[86:87]
	v_lshlrev_b32_e32 v128, 16, v183
	v_and_b32_e32 v129, 0xffff0000, v183
	v_pk_fma_f32 v[120:121], v[14:15], v[128:129], v[62:63]
	v_pk_fma_f32 v[104:105], v[30:31], v[128:129], v[104:105]
	v_pk_fma_f32 v[88:89], v[46:47], v[128:129], v[88:89]
	global_load_dwordx4 v[176:179], v[72:73], off nt
	v_lshl_add_u64 v[72:73], v[72:73], 0, s[10:11]
	global_load_dwordx4 v[180:183], v[72:73], off nt
	v_lshl_add_u64 v[72:73], v[72:73], 0, s[10:11]
	v_mul_f32_e32 v122, 0xbfb8aa3b, v74
	v_mul_f32_e32 v123, 0xbfb8aa3b, v75
	v_mul_f32_e32 v124, 0xbfb8aa3b, v76
	v_mul_f32_e32 v125, 0xbfb8aa3b, v77
	v_mul_f32_e32 v126, 0xbfb8aa3b, v78
	v_mul_f32_e32 v127, 0xbfb8aa3b, v79
	v_mul_f32_e32 v128, 0xbfb8aa3b, v80
	v_mul_f32_e32 v129, 0xbfb8aa3b, v81
; __device__ __forceinline__ uint4 ld_nt16(const void* p) { const u32x4_t t = __builtin_nontemporal_load((const u32x4_t*)p); return make_uint4(t[0], t[1], t[2], t[3]); }
; __device__ __forceinline__ unsigned pk2(float lo, float hi) { f32x2_t v = {lo, hi}; bf16x2_t b = __builtin_convertvector(v, bf16x2_t); return __builtin_bit_cast(unsigned, b); }
; __device__ __forceinline__ float lo_bf(unsigned u) { return __uint_as_float(u << 16); }
; __device__ __forceinline__ float hi_bf(unsigned u) { return __uint_as_float(u & 0xffff0000u); }
; __device__ __forceinline__ float siluf_(float x) { return x * __builtin_amdgcn_rcpf(1.f + __expf(-x)); }
; __device__ void conv_phase(int swave, const Params& p, int layer, int h) {
;     ...
;     for (int i = 0; i < 16; ++i) {
;       uint4 na = zero4, nv = zero4;
;       if (s0 + i + 1 < SEQ) { na = ld_nt16(base + (size_t)(i + 1) * ULD); nv = ld_nt16(base + (size_t)(i + 1) * ULD + FFNH); }
;       const unsigned rp[4] = {pa.x, pa.y, pa.z, pa.w}, rc[4] = {ca.x, ca.y, ca.z, ca.w}, rn[4] = {na.x, na.y, na.z, na.w};
;       const unsigned qp[4] = {pv.x, pv.y, pv.z, pv.w}, qc[4] = {cv.x, cv.y, cv.z, cv.w}, qn[4] = {nv.x, nv.y, nv.z, nv.w};
;       float oa[8], ov[8];
; #pragma unroll
;       for (int e = 0; e < 4; ++e) {
;         oa[2 * e] = ba[2 * e] + lo_bf(rp[e]) * wa[0][2 * e] + lo_bf(rc[e]) * wa[1][2 * e] + lo_bf(rn[e]) * wa[2][2 * e];
;         oa[2 * e + 1] = ba[2 * e + 1] + hi_bf(rp[e]) * wa[0][2 * e + 1] + hi_bf(rc[e]) * wa[1][2 * e + 1] + hi_bf(rn[e]) * wa[2][2 * e + 1];
;         ov[2 * e] = bv[2 * e] + lo_bf(qp[e]) * wv[0][2 * e] + lo_bf(qc[e]) * wv[1][2 * e] + lo_bf(qn[e]) * wv[2][2 * e];
;         ov[2 * e + 1] = bv[2 * e + 1] + hi_bf(qp[e]) * wv[0][2 * e + 1] + hi_bf(qc[e]) * wv[1][2 * e + 1] + hi_bf(qn[e]) * wv[2][2 * e + 1];
;       }
;       uint4 o;
;       o.x = pk2(siluf_(oa[0]) * ov[0], siluf_(oa[1]) * ov[1]); o.y = pk2(siluf_(oa[2]) * ov[2], siluf_(oa[3]) * ov[3]);
;       o.z = pk2(siluf_(oa[4]) * ov[4], siluf_(oa[5]) * ov[5]); o.w = pk2(siluf_(oa[6]) * ov[6], siluf_(oa[7]) * ov[7]);
;       *(uint4*)(ACT + (size_t)(t0 + i) * FFNH + f8) = o;
;       pa = ca; pv = cv; ca = na; cv = nv;
	v_exp_f32_e32 v122, v122
	v_exp_f32_e32 v123, v123
	v_exp_f32_e32 v124, v124
	v_exp_f32_e32 v125, v125
	v_exp_f32_e32 v126, v126
	v_exp_f32_e32 v127, v127
	v_exp_f32_e32 v128, v128
	v_exp_f32_e32 v129, v129
	v_add_f32_e32 v122, 1.0, v122
	v_add_f32_e32 v123, 1.0, v123
	v_add_f32_e32 v124, 1.0, v124
	v_add_f32_e32 v125, 1.0, v125
	v_add_f32_e32 v126, 1.0, v126
	v_add_f32_e32 v127, 1.0, v127
	v_add_f32_e32 v128, 1.0, v128
	v_add_f32_e32 v129, 1.0, v129
	v_rcp_f32_e32 v122, v122
	v_rcp_f32_e32 v123, v123
	v_rcp_f32_e32 v124, v124
	v_rcp_f32_e32 v125, v125
	v_rcp_f32_e32 v126, v126
	v_rcp_f32_e32 v127, v127
	v_rcp_f32_e32 v128, v128
	v_rcp_f32_e32 v129, v129
	v_pk_mul_f32 v[74:75], v[74:75], v[122:123]
	v_pk_mul_f32 v[76:77], v[76:77], v[124:125]
	v_pk_mul_f32 v[78:79], v[78:79], v[126:127]
	v_pk_mul_f32 v[80:81], v[80:81], v[128:129]
	v_pk_mul_f32 v[74:75], v[82:83], v[74:75]
	v_pk_mul_f32 v[76:77], v[84:85], v[76:77]
	v_pk_mul_f32 v[78:79], v[86:87], v[78:79]
	v_pk_mul_f32 v[80:81], v[88:89], v[80:81]
	v_cvt_pk_bf16_f32 v138, v74, v75
	v_cvt_pk_bf16_f32 v139, v76, v77
	v_cvt_pk_bf16_f32 v140, v78, v79
	v_cvt_pk_bf16_f32 v141, v80, v81
	global_store_dwordx4 v[70:71], v[138:141], off
	v_lshl_add_u64 v[70:71], v[70:71], 0, s[10:11]
	v_lshlrev_b32_e32 v126, 16, v184
	v_and_b32_e32 v127, 0xffff0000, v184
	v_pk_fma_f32 v[74:75], v[8:9], v[126:127], v[56:57]
	v_pk_fma_f32 v[106:107], v[24:25], v[126:127], v[106:107]
	v_pk_fma_f32 v[90:91], v[40:41], v[126:127], v[90:91]
	v_lshlrev_b32_e32 v128, 16, v185
	v_and_b32_e32 v129, 0xffff0000, v185
	v_pk_fma_f32 v[76:77], v[10:11], v[128:129], v[58:59]
	v_pk_fma_f32 v[108:109], v[26:27], v[128:129], v[108:109]
	v_pk_fma_f32 v[92:93], v[42:43], v[128:129], v[92:93]
	v_lshlrev_b32_e32 v126, 16, v186
	v_and_b32_e32 v127, 0xffff0000, v186
	v_pk_fma_f32 v[78:79], v[4:5], v[126:127], v[52:53]
	v_pk_fma_f32 v[110:111], v[20:21], v[126:127], v[110:111]
	v_pk_fma_f32 v[94:95], v[36:37], v[126:127], v[94:95]
	v_lshlrev_b32_e32 v128, 16, v187
	v_and_b32_e32 v129, 0xffff0000, v187
	v_pk_fma_f32 v[80:81], v[6:7], v[128:129], v[54:55]
	v_pk_fma_f32 v[112:113], v[22:23], v[128:129], v[112:113]
	v_pk_fma_f32 v[96:97], v[38:39], v[128:129], v[96:97]
	v_lshlrev_b32_e32 v126, 16, v188
	v_and_b32_e32 v127, 0xffff0000, v188
	v_pk_fma_f32 v[82:83], v[16:17], v[126:127], v[64:65]
	v_pk_fma_f32 v[114:115], v[32:33], v[126:127], v[114:115]
	v_pk_fma_f32 v[98:99], v[48:49], v[126:127], v[98:99]
	v_lshlrev_b32_e32 v128, 16, v189
	v_and_b32_e32 v129, 0xffff0000, v189
	v_pk_fma_f32 v[84:85], v[18:19], v[128:129], v[66:67]
	v_pk_fma_f32 v[116:117], v[34:35], v[128:129], v[116:117]
	v_pk_fma_f32 v[100:101], v[50:51], v[128:129], v[100:101]
	v_lshlrev_b32_e32 v126, 16, v190
	v_and_b32_e32 v127, 0xffff0000, v190
	v_pk_fma_f32 v[86:87], v[12:13], v[126:127], v[60:61]
	v_pk_fma_f32 v[118:119], v[28:29], v[126:127], v[118:119]
	v_pk_fma_f32 v[102:103], v[44:45], v[126:127], v[102:103]
	v_lshlrev_b32_e32 v128, 16, v191
	v_and_b32_e32 v129, 0xffff0000, v191
	v_pk_fma_f32 v[88:89], v[14:15], v[128:129], v[62:63]
	v_pk_fma_f32 v[120:121], v[30:31], v[128:129], v[120:121]
	v_pk_fma_f32 v[104:105], v[46:47], v[128:129], v[104:105]
	global_load_dwordx4 v[184:187], v[72:73], off nt
	v_lshl_add_u64 v[72:73], v[72:73], 0, s[10:11]
	global_load_dwordx4 v[188:191], v[72:73], off nt
	v_lshl_add_u64 v[72:73], v[72:73], 0, s[10:11]
	v_mul_f32_e32 v122, 0xbfb8aa3b, v90
	v_mul_f32_e32 v123, 0xbfb8aa3b, v91
	v_mul_f32_e32 v124, 0xbfb8aa3b, v92
	v_mul_f32_e32 v125, 0xbfb8aa3b, v93
	v_mul_f32_e32 v126, 0xbfb8aa3b, v94
	v_mul_f32_e32 v127, 0xbfb8aa3b, v95
	v_mul_f32_e32 v128, 0xbfb8aa3b, v96
	v_mul_f32_e32 v129, 0xbfb8aa3b, v97
	v_exp_f32_e32 v122, v122
	v_exp_f32_e32 v123, v123
	v_exp_f32_e32 v124, v124
	v_exp_f32_e32 v125, v125
	v_exp_f32_e32 v126, v126
	v_exp_f32_e32 v127, v127
	v_exp_f32_e32 v128, v128
	v_exp_f32_e32 v129, v129
	v_add_f32_e32 v122, 1.0, v122
	v_add_f32_e32 v123, 1.0, v123
	v_add_f32_e32 v124, 1.0, v124
	v_add_f32_e32 v125, 1.0, v125
	v_add_f32_e32 v126, 1.0, v126
	v_add_f32_e32 v127, 1.0, v127
	v_add_f32_e32 v128, 1.0, v128
	v_add_f32_e32 v129, 1.0, v129
	v_rcp_f32_e32 v122, v122
	v_rcp_f32_e32 v123, v123
	v_rcp_f32_e32 v124, v124
	v_rcp_f32_e32 v125, v125
	v_rcp_f32_e32 v126, v126
	v_rcp_f32_e32 v127, v127
	v_rcp_f32_e32 v128, v128
	v_rcp_f32_e32 v129, v129
	v_pk_mul_f32 v[90:91], v[90:91], v[122:123]
	v_pk_mul_f32 v[92:93], v[92:93], v[124:125]
	v_pk_mul_f32 v[94:95], v[94:95], v[126:127]
	v_pk_mul_f32 v[96:97], v[96:97], v[128:129]
	v_pk_mul_f32 v[90:91], v[98:99], v[90:91]
	v_pk_mul_f32 v[92:93], v[100:101], v[92:93]
	v_pk_mul_f32 v[94:95], v[102:103], v[94:95]
	v_pk_mul_f32 v[96:97], v[104:105], v[96:97]
	v_cvt_pk_bf16_f32 v138, v90, v91
	v_cvt_pk_bf16_f32 v139, v92, v93
	v_cvt_pk_bf16_f32 v140, v94, v95
	v_cvt_pk_bf16_f32 v141, v96, v97
	global_store_dwordx4 v[70:71], v[138:141], off
	v_lshl_add_u64 v[70:71], v[70:71], 0, s[10:11]
	v_lshlrev_b32_e32 v126, 16, v192
	v_and_b32_e32 v127, 0xffff0000, v192
	v_pk_fma_f32 v[90:91], v[8:9], v[126:127], v[56:57]
	v_pk_fma_f32 v[74:75], v[24:25], v[126:127], v[74:75]
	v_pk_fma_f32 v[106:107], v[40:41], v[126:127], v[106:107]
	v_lshlrev_b32_e32 v128, 16, v193
	v_and_b32_e32 v129, 0xffff0000, v193
	v_pk_fma_f32 v[92:93], v[10:11], v[128:129], v[58:59]
	v_pk_fma_f32 v[76:77], v[26:27], v[128:129], v[76:77]
	v_pk_fma_f32 v[108:109], v[42:43], v[128:129], v[108:109]
	v_lshlrev_b32_e32 v126, 16, v194
	v_and_b32_e32 v127, 0xffff0000, v194
	v_pk_fma_f32 v[94:95], v[4:5], v[126:127], v[52:53]
	v_pk_fma_f32 v[78:79], v[20:21], v[126:127], v[78:79]
	v_pk_fma_f32 v[110:111], v[36:37], v[126:127], v[110:111]
; __device__ __forceinline__ uint4 ld_nt16(const void* p) { const u32x4_t t = __builtin_nontemporal_load((const u32x4_t*)p); return make_uint4(t[0], t[1], t[2], t[3]); }
; __device__ __forceinline__ unsigned pk2(float lo, float hi) { f32x2_t v = {lo, hi}; bf16x2_t b = __builtin_convertvector(v, bf16x2_t); return __builtin_bit_cast(unsigned, b); }
; __device__ __forceinline__ float lo_bf(unsigned u) { return __uint_as_float(u << 16); }
; __device__ __forceinline__ float hi_bf(unsigned u) { return __uint_as_float(u & 0xffff0000u); }
; __device__ __forceinline__ float siluf_(float x) { return x * __builtin_amdgcn_rcpf(1.f + __expf(-x)); }
; __device__ void conv_phase(int swave, const Params& p, int layer, int h) {
;     ...
;     for (int i = 0; i < 16; ++i) {
;       uint4 na = zero4, nv = zero4;
;       if (s0 + i + 1 < SEQ) { na = ld_nt16(base + (size_t)(i + 1) * ULD); nv = ld_nt16(base + (size_t)(i + 1) * ULD + FFNH); }
;       const unsigned rp[4] = {pa.x, pa.y, pa.z, pa.w}, rc[4] = {ca.x, ca.y, ca.z, ca.w}, rn[4] = {na.x, na.y, na.z, na.w};
;       const unsigned qp[4] = {pv.x, pv.y, pv.z, pv.w}, qc[4] = {cv.x, cv.y, cv.z, cv.w}, qn[4] = {nv.x, nv.y, nv.z, nv.w};
;       float oa[8], ov[8];
; #pragma unroll
;       for (int e = 0; e < 4; ++e) {
;         oa[2 * e] = ba[2 * e] + lo_bf(rp[e]) * wa[0][2 * e] + lo_bf(rc[e]) * wa[1][2 * e] + lo_bf(rn[e]) * wa[2][2 * e];
;         oa[2 * e + 1] = ba[2 * e + 1] + hi_bf(rp[e]) * wa[0][2 * e + 1] + hi_bf(rc[e]) * wa[1][2 * e + 1] + hi_bf(rn[e]) * wa[2][2 * e + 1];
;         ov[2 * e] = bv[2 * e] + lo_bf(qp[e]) * wv[0][2 * e] + lo_bf(qc[e]) * wv[1][2 * e] + lo_bf(qn[e]) * wv[2][2 * e];
;         ov[2 * e + 1] = bv[2 * e + 1] + hi_bf(qp[e]) * wv[0][2 * e + 1] + hi_bf(qc[e]) * wv[1][2 * e + 1] + hi_bf(qn[e]) * wv[2][2 * e + 1];
;       }
;       uint4 o;
;       o.x = pk2(siluf_(oa[0]) * ov[0], siluf_(oa[1]) * ov[1]); o.y = pk2(siluf_(oa[2]) * ov[2], siluf_(oa[3]) * ov[3]);
;       o.z = pk2(siluf_(oa[4]) * ov[4], siluf_(oa[5]) * ov[5]); o.w = pk2(siluf_(oa[6]) * ov[6], siluf_(oa[7]) * ov[7]);
;       *(uint4*)(ACT + (size_t)(t0 + i) * FFNH + f8) = o;
;       pa = ca; pv = cv; ca = na; cv = nv;
	v_lshlrev_b32_e32 v128, 16, v195
	v_and_b32_e32 v129, 0xffff0000, v195
	v_pk_fma_f32 v[96:97], v[6:7], v[128:129], v[54:55]
	v_pk_fma_f32 v[80:81], v[22:23], v[128:129], v[80:81]
	v_pk_fma_f32 v[112:113], v[38:39], v[128:129], v[112:113]
	v_lshlrev_b32_e32 v126, 16, v196
	v_and_b32_e32 v127, 0xffff0000, v196
	v_pk_fma_f32 v[98:99], v[16:17], v[126:127], v[64:65]
	v_pk_fma_f32 v[82:83], v[32:33], v[126:127], v[82:83]
	v_pk_fma_f32 v[114:115], v[48:49], v[126:127], v[114:115]
	v_lshlrev_b32_e32 v128, 16, v197
	v_and_b32_e32 v129, 0xffff0000, v197
	v_pk_fma_f32 v[100:101], v[18:19], v[128:129], v[66:67]
	v_pk_fma_f32 v[84:85], v[34:35], v[128:129], v[84:85]
	v_pk_fma_f32 v[116:117], v[50:51], v[128:129], v[116:117]
	v_lshlrev_b32_e32 v126, 16, v198
	v_and_b32_e32 v127, 0xffff0000, v198
	v_pk_fma_f32 v[102:103], v[12:13], v[126:127], v[60:61]
	v_pk_fma_f32 v[86:87], v[28:29], v[126:127], v[86:87]
	v_pk_fma_f32 v[118:119], v[44:45], v[126:127], v[118:119]
	v_lshlrev_b32_e32 v128, 16, v199
	v_and_b32_e32 v129, 0xffff0000, v199
	v_pk_fma_f32 v[104:105], v[14:15], v[128:129], v[62:63]
	v_pk_fma_f32 v[88:89], v[30:31], v[128:129], v[88:89]
	v_pk_fma_f32 v[120:121], v[46:47], v[128:129], v[120:121]
	global_load_dwordx4 v[192:195], v[72:73], off nt
	v_lshl_add_u64 v[72:73], v[72:73], 0, s[10:11]
	global_load_dwordx4 v[196:199], v[72:73], off nt
	v_lshl_add_u64 v[72:73], v[72:73], 0, s[10:11]
	v_mul_f32_e32 v122, 0xbfb8aa3b, v106
	v_mul_f32_e32 v123, 0xbfb8aa3b, v107
	v_mul_f32_e32 v124, 0xbfb8aa3b, v108
	v_mul_f32_e32 v125, 0xbfb8aa3b, v109
	v_mul_f32_e32 v126, 0xbfb8aa3b, v110
	v_mul_f32_e32 v127, 0xbfb8aa3b, v111
	v_mul_f32_e32 v128, 0xbfb8aa3b, v112
	v_mul_f32_e32 v129, 0xbfb8aa3b, v113
	v_exp_f32_e32 v122, v122
	v_exp_f32_e32 v123, v123
	v_exp_f32_e32 v124, v124
	v_exp_f32_e32 v125, v125
	v_exp_f32_e32 v126, v126
	v_exp_f32_e32 v127, v127
	v_exp_f32_e32 v128, v128
	v_exp_f32_e32 v129, v129
	v_add_f32_e32 v122, 1.0, v122
	v_add_f32_e32 v123, 1.0, v123
	v_add_f32_e32 v124, 1.0, v124
	v_add_f32_e32 v125, 1.0, v125
	v_add_f32_e32 v126, 1.0, v126
	v_add_f32_e32 v127, 1.0, v127
	v_add_f32_e32 v128, 1.0, v128
	v_add_f32_e32 v129, 1.0, v129
	v_rcp_f32_e32 v122, v122
	v_rcp_f32_e32 v123, v123
	v_rcp_f32_e32 v124, v124
	v_rcp_f32_e32 v125, v125
	v_rcp_f32_e32 v126, v126
	v_rcp_f32_e32 v127, v127
	v_rcp_f32_e32 v128, v128
	v_rcp_f32_e32 v129, v129
	v_pk_mul_f32 v[106:107], v[106:107], v[122:123]
	v_pk_mul_f32 v[108:109], v[108:109], v[124:125]
	v_pk_mul_f32 v[110:111], v[110:111], v[126:127]
	v_pk_mul_f32 v[112:113], v[112:113], v[128:129]
	v_pk_mul_f32 v[106:107], v[114:115], v[106:107]
	v_pk_mul_f32 v[108:109], v[116:117], v[108:109]
	v_pk_mul_f32 v[110:111], v[118:119], v[110:111]
	v_pk_mul_f32 v[112:113], v[120:121], v[112:113]
	v_cvt_pk_bf16_f32 v138, v106, v107
	v_cvt_pk_bf16_f32 v139, v108, v109
	v_cvt_pk_bf16_f32 v140, v110, v111
	v_cvt_pk_bf16_f32 v141, v112, v113
	global_store_dwordx4 v[70:71], v[138:141], off
	v_lshl_add_u64 v[70:71], v[70:71], 0, s[10:11]
	v_lshlrev_b32_e32 v126, 16, v200
	v_and_b32_e32 v127, 0xffff0000, v200
	v_pk_fma_f32 v[106:107], v[8:9], v[126:127], v[56:57]
	v_pk_fma_f32 v[90:91], v[24:25], v[126:127], v[90:91]
	v_pk_fma_f32 v[74:75], v[40:41], v[126:127], v[74:75]
	v_lshlrev_b32_e32 v128, 16, v201
	v_and_b32_e32 v129, 0xffff0000, v201
	v_pk_fma_f32 v[108:109], v[10:11], v[128:129], v[58:59]
	v_pk_fma_f32 v[92:93], v[26:27], v[128:129], v[92:93]
	v_pk_fma_f32 v[76:77], v[42:43], v[128:129], v[76:77]
	v_lshlrev_b32_e32 v126, 16, v202
	v_and_b32_e32 v127, 0xffff0000, v202
	v_pk_fma_f32 v[110:111], v[4:5], v[126:127], v[52:53]
	v_pk_fma_f32 v[94:95], v[20:21], v[126:127], v[94:95]
	v_pk_fma_f32 v[78:79], v[36:37], v[126:127], v[78:79]
	v_lshlrev_b32_e32 v128, 16, v203
	v_and_b32_e32 v129, 0xffff0000, v203
	v_pk_fma_f32 v[112:113], v[6:7], v[128:129], v[54:55]
	v_pk_fma_f32 v[96:97], v[22:23], v[128:129], v[96:97]
	v_pk_fma_f32 v[80:81], v[38:39], v[128:129], v[80:81]
	v_lshlrev_b32_e32 v126, 16, v204
	v_and_b32_e32 v127, 0xffff0000, v204
	v_pk_fma_f32 v[114:115], v[16:17], v[126:127], v[64:65]
	v_pk_fma_f32 v[98:99], v[32:33], v[126:127], v[98:99]
	v_pk_fma_f32 v[82:83], v[48:49], v[126:127], v[82:83]
	v_lshlrev_b32_e32 v128, 16, v205
	v_and_b32_e32 v129, 0xffff0000, v205
	v_pk_fma_f32 v[116:117], v[18:19], v[128:129], v[66:67]
	v_pk_fma_f32 v[100:101], v[34:35], v[128:129], v[100:101]
	v_pk_fma_f32 v[84:85], v[50:51], v[128:129], v[84:85]
	v_lshlrev_b32_e32 v126, 16, v206
	v_and_b32_e32 v127, 0xffff0000, v206
	v_pk_fma_f32 v[118:119], v[12:13], v[126:127], v[60:61]
	v_pk_fma_f32 v[102:103], v[28:29], v[126:127], v[102:103]
	v_pk_fma_f32 v[86:87], v[44:45], v[126:127], v[86:87]
	v_lshlrev_b32_e32 v128, 16, v207
	v_and_b32_e32 v129, 0xffff0000, v207
	v_pk_fma_f32 v[120:121], v[14:15], v[128:129], v[62:63]
	v_pk_fma_f32 v[104:105], v[30:31], v[128:129], v[104:105]
	v_pk_fma_f32 v[88:89], v[46:47], v[128:129], v[88:89]
	global_load_dwordx4 v[200:203], v[72:73], off nt
	v_lshl_add_u64 v[72:73], v[72:73], 0, s[10:11]
	global_load_dwordx4 v[204:207], v[72:73], off nt
	v_lshl_add_u64 v[72:73], v[72:73], 0, s[10:11]
	v_mul_f32_e32 v122, 0xbfb8aa3b, v74
	v_mul_f32_e32 v123, 0xbfb8aa3b, v75
	v_mul_f32_e32 v124, 0xbfb8aa3b, v76
	v_mul_f32_e32 v125, 0xbfb8aa3b, v77
	v_mul_f32_e32 v126, 0xbfb8aa3b, v78
	v_mul_f32_e32 v127, 0xbfb8aa3b, v79
	v_mul_f32_e32 v128, 0xbfb8aa3b, v80
	v_mul_f32_e32 v129, 0xbfb8aa3b, v81
	v_exp_f32_e32 v122, v122
	v_exp_f32_e32 v123, v123
	v_exp_f32_e32 v124, v124
	v_exp_f32_e32 v125, v125
	v_exp_f32_e32 v126, v126
	v_exp_f32_e32 v127, v127
	v_exp_f32_e32 v128, v128
	v_exp_f32_e32 v129, v129
	v_add_f32_e32 v122, 1.0, v122
; __device__ __forceinline__ uint4 ld_nt16(const void* p) { const u32x4_t t = __builtin_nontemporal_load((const u32x4_t*)p); return make_uint4(t[0], t[1], t[2], t[3]); }
; __device__ __forceinline__ unsigned pk2(float lo, float hi) { f32x2_t v = {lo, hi}; bf16x2_t b = __builtin_convertvector(v, bf16x2_t); return __builtin_bit_cast(unsigned, b); }
; __device__ __forceinline__ float lo_bf(unsigned u) { return __uint_as_float(u << 16); }
; __device__ __forceinline__ float hi_bf(unsigned u) { return __uint_as_float(u & 0xffff0000u); }
; __device__ __forceinline__ float siluf_(float x) { return x * __builtin_amdgcn_rcpf(1.f + __expf(-x)); }
; __device__ void conv_phase(int swave, const Params& p, int layer, int h) {
;     ...
;     for (int i = 0; i < 16; ++i) {
;       uint4 na = zero4, nv = zero4;
;       if (s0 + i + 1 < SEQ) { na = ld_nt16(base + (size_t)(i + 1) * ULD); nv = ld_nt16(base + (size_t)(i + 1) * ULD + FFNH); }
;       const unsigned rp[4] = {pa.x, pa.y, pa.z, pa.w}, rc[4] = {ca.x, ca.y, ca.z, ca.w}, rn[4] = {na.x, na.y, na.z, na.w};
;       const unsigned qp[4] = {pv.x, pv.y, pv.z, pv.w}, qc[4] = {cv.x, cv.y, cv.z, cv.w}, qn[4] = {nv.x, nv.y, nv.z, nv.w};
;       float oa[8], ov[8];
; #pragma unroll
;       for (int e = 0; e < 4; ++e) {
;         oa[2 * e] = ba[2 * e] + lo_bf(rp[e]) * wa[0][2 * e] + lo_bf(rc[e]) * wa[1][2 * e] + lo_bf(rn[e]) * wa[2][2 * e];
;         oa[2 * e + 1] = ba[2 * e + 1] + hi_bf(rp[e]) * wa[0][2 * e + 1] + hi_bf(rc[e]) * wa[1][2 * e + 1] + hi_bf(rn[e]) * wa[2][2 * e + 1];
;         ov[2 * e] = bv[2 * e] + lo_bf(qp[e]) * wv[0][2 * e] + lo_bf(qc[e]) * wv[1][2 * e] + lo_bf(qn[e]) * wv[2][2 * e];
;         ov[2 * e + 1] = bv[2 * e + 1] + hi_bf(qp[e]) * wv[0][2 * e + 1] + hi_bf(qc[e]) * wv[1][2 * e + 1] + hi_bf(qn[e]) * wv[2][2 * e + 1];
;       }
;       uint4 o;
;       o.x = pk2(siluf_(oa[0]) * ov[0], siluf_(oa[1]) * ov[1]); o.y = pk2(siluf_(oa[2]) * ov[2], siluf_(oa[3]) * ov[3]);
;       o.z = pk2(siluf_(oa[4]) * ov[4], siluf_(oa[5]) * ov[5]); o.w = pk2(siluf_(oa[6]) * ov[6], siluf_(oa[7]) * ov[7]);
;       *(uint4*)(ACT + (size_t)(t0 + i) * FFNH + f8) = o;
;       pa = ca; pv = cv; ca = na; cv = nv;
	v_add_f32_e32 v123, 1.0, v123
	v_add_f32_e32 v124, 1.0, v124
	v_add_f32_e32 v125, 1.0, v125
	v_add_f32_e32 v126, 1.0, v126
	v_add_f32_e32 v127, 1.0, v127
	v_add_f32_e32 v128, 1.0, v128
	v_add_f32_e32 v129, 1.0, v129
	v_rcp_f32_e32 v122, v122
	v_rcp_f32_e32 v123, v123
	v_rcp_f32_e32 v124, v124
	v_rcp_f32_e32 v125, v125
	v_rcp_f32_e32 v126, v126
	v_rcp_f32_e32 v127, v127
	v_rcp_f32_e32 v128, v128
	v_rcp_f32_e32 v129, v129
	v_pk_mul_f32 v[74:75], v[74:75], v[122:123]
	v_pk_mul_f32 v[76:77], v[76:77], v[124:125]
	v_pk_mul_f32 v[78:79], v[78:79], v[126:127]
	v_pk_mul_f32 v[80:81], v[80:81], v[128:129]
	v_pk_mul_f32 v[74:75], v[82:83], v[74:75]
	v_pk_mul_f32 v[76:77], v[84:85], v[76:77]
	v_pk_mul_f32 v[78:79], v[86:87], v[78:79]
	v_pk_mul_f32 v[80:81], v[88:89], v[80:81]
	v_cvt_pk_bf16_f32 v138, v74, v75
	v_cvt_pk_bf16_f32 v139, v76, v77
	v_cvt_pk_bf16_f32 v140, v78, v79
	v_cvt_pk_bf16_f32 v141, v80, v81
	global_store_dwordx4 v[70:71], v[138:141], off
	v_lshl_add_u64 v[70:71], v[70:71], 0, s[10:11]
	v_lshlrev_b32_e32 v126, 16, v208
	v_and_b32_e32 v127, 0xffff0000, v208
	v_pk_fma_f32 v[74:75], v[8:9], v[126:127], v[56:57]
	v_pk_fma_f32 v[106:107], v[24:25], v[126:127], v[106:107]
	v_pk_fma_f32 v[90:91], v[40:41], v[126:127], v[90:91]
	v_lshlrev_b32_e32 v128, 16, v209
	v_and_b32_e32 v129, 0xffff0000, v209
	v_pk_fma_f32 v[76:77], v[10:11], v[128:129], v[58:59]
	v_pk_fma_f32 v[108:109], v[26:27], v[128:129], v[108:109]
	v_pk_fma_f32 v[92:93], v[42:43], v[128:129], v[92:93]
	v_lshlrev_b32_e32 v126, 16, v210
	v_and_b32_e32 v127, 0xffff0000, v210
	v_pk_fma_f32 v[78:79], v[4:5], v[126:127], v[52:53]
	v_pk_fma_f32 v[110:111], v[20:21], v[126:127], v[110:111]
	v_pk_fma_f32 v[94:95], v[36:37], v[126:127], v[94:95]
	v_lshlrev_b32_e32 v128, 16, v211
	v_and_b32_e32 v129, 0xffff0000, v211
	v_pk_fma_f32 v[80:81], v[6:7], v[128:129], v[54:55]
	v_pk_fma_f32 v[112:113], v[22:23], v[128:129], v[112:113]
	v_pk_fma_f32 v[96:97], v[38:39], v[128:129], v[96:97]
	v_lshlrev_b32_e32 v126, 16, v212
	v_and_b32_e32 v127, 0xffff0000, v212
	v_pk_fma_f32 v[82:83], v[16:17], v[126:127], v[64:65]
	v_pk_fma_f32 v[114:115], v[32:33], v[126:127], v[114:115]
	v_pk_fma_f32 v[98:99], v[48:49], v[126:127], v[98:99]
	v_lshlrev_b32_e32 v128, 16, v213
	v_and_b32_e32 v129, 0xffff0000, v213
	v_pk_fma_f32 v[84:85], v[18:19], v[128:129], v[66:67]
	v_pk_fma_f32 v[116:117], v[34:35], v[128:129], v[116:117]
	v_pk_fma_f32 v[100:101], v[50:51], v[128:129], v[100:101]
	v_lshlrev_b32_e32 v126, 16, v214
	v_and_b32_e32 v127, 0xffff0000, v214
	v_pk_fma_f32 v[86:87], v[12:13], v[126:127], v[60:61]
	v_pk_fma_f32 v[118:119], v[28:29], v[126:127], v[118:119]
	v_pk_fma_f32 v[102:103], v[44:45], v[126:127], v[102:103]
	v_lshlrev_b32_e32 v128, 16, v215
	v_and_b32_e32 v129, 0xffff0000, v215
	v_pk_fma_f32 v[88:89], v[14:15], v[128:129], v[62:63]
	v_pk_fma_f32 v[120:121], v[30:31], v[128:129], v[120:121]
	v_pk_fma_f32 v[104:105], v[46:47], v[128:129], v[104:105]
	global_load_dwordx4 v[208:211], v[72:73], off nt
	v_lshl_add_u64 v[72:73], v[72:73], 0, s[10:11]
	global_load_dwordx4 v[212:215], v[72:73], off nt
	v_lshl_add_u64 v[72:73], v[72:73], 0, s[10:11]
	v_mul_f32_e32 v122, 0xbfb8aa3b, v90
	v_mul_f32_e32 v123, 0xbfb8aa3b, v91
	v_mul_f32_e32 v124, 0xbfb8aa3b, v92
	v_mul_f32_e32 v125, 0xbfb8aa3b, v93
	v_mul_f32_e32 v126, 0xbfb8aa3b, v94
	v_mul_f32_e32 v127, 0xbfb8aa3b, v95
	v_mul_f32_e32 v128, 0xbfb8aa3b, v96
	v_mul_f32_e32 v129, 0xbfb8aa3b, v97
	v_exp_f32_e32 v122, v122
	v_exp_f32_e32 v123, v123
	v_exp_f32_e32 v124, v124
	v_exp_f32_e32 v125, v125
	v_exp_f32_e32 v126, v126
	v_exp_f32_e32 v127, v127
	v_exp_f32_e32 v128, v128
	v_exp_f32_e32 v129, v129
	v_add_f32_e32 v122, 1.0, v122
	v_add_f32_e32 v123, 1.0, v123
	v_add_f32_e32 v124, 1.0, v124
	v_add_f32_e32 v125, 1.0, v125
	v_add_f32_e32 v126, 1.0, v126
	v_add_f32_e32 v127, 1.0, v127
	v_add_f32_e32 v128, 1.0, v128
	v_add_f32_e32 v129, 1.0, v129
	v_rcp_f32_e32 v122, v122
	v_rcp_f32_e32 v123, v123
	v_rcp_f32_e32 v124, v124
	v_rcp_f32_e32 v125, v125
	v_rcp_f32_e32 v126, v126
	v_rcp_f32_e32 v127, v127
	v_rcp_f32_e32 v128, v128
	v_rcp_f32_e32 v129, v129
	v_pk_mul_f32 v[90:91], v[90:91], v[122:123]
	v_pk_mul_f32 v[92:93], v[92:93], v[124:125]
	v_pk_mul_f32 v[94:95], v[94:95], v[126:127]
	v_pk_mul_f32 v[96:97], v[96:97], v[128:129]
	v_pk_mul_f32 v[90:91], v[98:99], v[90:91]
	v_pk_mul_f32 v[92:93], v[100:101], v[92:93]
	v_pk_mul_f32 v[94:95], v[102:103], v[94:95]
	v_pk_mul_f32 v[96:97], v[104:105], v[96:97]
	v_cvt_pk_bf16_f32 v138, v90, v91
	v_cvt_pk_bf16_f32 v139, v92, v93
	v_cvt_pk_bf16_f32 v140, v94, v95
	v_cvt_pk_bf16_f32 v141, v96, v97
	global_store_dwordx4 v[70:71], v[138:141], off
	v_lshl_add_u64 v[70:71], v[70:71], 0, s[10:11]
	v_lshlrev_b32_e32 v126, 16, v216
	v_and_b32_e32 v127, 0xffff0000, v216
	v_pk_fma_f32 v[90:91], v[8:9], v[126:127], v[56:57]
	v_pk_fma_f32 v[74:75], v[24:25], v[126:127], v[74:75]
	v_pk_fma_f32 v[106:107], v[40:41], v[126:127], v[106:107]
	v_lshlrev_b32_e32 v128, 16, v217
	v_and_b32_e32 v129, 0xffff0000, v217
	v_pk_fma_f32 v[92:93], v[10:11], v[128:129], v[58:59]
	v_pk_fma_f32 v[76:77], v[26:27], v[128:129], v[76:77]
	v_pk_fma_f32 v[108:109], v[42:43], v[128:129], v[108:109]
	v_lshlrev_b32_e32 v126, 16, v218
	v_and_b32_e32 v127, 0xffff0000, v218
	v_pk_fma_f32 v[94:95], v[4:5], v[126:127], v[52:53]
	v_pk_fma_f32 v[78:79], v[20:21], v[126:127], v[78:79]
	v_pk_fma_f32 v[110:111], v[36:37], v[126:127], v[110:111]
	v_lshlrev_b32_e32 v128, 16, v219
	v_and_b32_e32 v129, 0xffff0000, v219
	v_pk_fma_f32 v[96:97], v[6:7], v[128:129], v[54:55]
	v_pk_fma_f32 v[80:81], v[22:23], v[128:129], v[80:81]
	v_pk_fma_f32 v[112:113], v[38:39], v[128:129], v[112:113]
; __device__ __forceinline__ uint4 ld_nt16(const void* p) { const u32x4_t t = __builtin_nontemporal_load((const u32x4_t*)p); return make_uint4(t[0], t[1], t[2], t[3]); }
; __device__ __forceinline__ unsigned pk2(float lo, float hi) { f32x2_t v = {lo, hi}; bf16x2_t b = __builtin_convertvector(v, bf16x2_t); return __builtin_bit_cast(unsigned, b); }
; __device__ __forceinline__ float lo_bf(unsigned u) { return __uint_as_float(u << 16); }
; __device__ __forceinline__ float hi_bf(unsigned u) { return __uint_as_float(u & 0xffff0000u); }
; __device__ __forceinline__ float siluf_(float x) { return x * __builtin_amdgcn_rcpf(1.f + __expf(-x)); }
; __device__ void conv_phase(int swave, const Params& p, int layer, int h) {
;     ...
;     for (int i = 0; i < 16; ++i) {
;       uint4 na = zero4, nv = zero4;
;       if (s0 + i + 1 < SEQ) { na = ld_nt16(base + (size_t)(i + 1) * ULD); nv = ld_nt16(base + (size_t)(i + 1) * ULD + FFNH); }
;       const unsigned rp[4] = {pa.x, pa.y, pa.z, pa.w}, rc[4] = {ca.x, ca.y, ca.z, ca.w}, rn[4] = {na.x, na.y, na.z, na.w};
;       const unsigned qp[4] = {pv.x, pv.y, pv.z, pv.w}, qc[4] = {cv.x, cv.y, cv.z, cv.w}, qn[4] = {nv.x, nv.y, nv.z, nv.w};
;       float oa[8], ov[8];
; #pragma unroll
;       for (int e = 0; e < 4; ++e) {
;         oa[2 * e] = ba[2 * e] + lo_bf(rp[e]) * wa[0][2 * e] + lo_bf(rc[e]) * wa[1][2 * e] + lo_bf(rn[e]) * wa[2][2 * e];
;         oa[2 * e + 1] = ba[2 * e + 1] + hi_bf(rp[e]) * wa[0][2 * e + 1] + hi_bf(rc[e]) * wa[1][2 * e + 1] + hi_bf(rn[e]) * wa[2][2 * e + 1];
;         ov[2 * e] = bv[2 * e] + lo_bf(qp[e]) * wv[0][2 * e] + lo_bf(qc[e]) * wv[1][2 * e] + lo_bf(qn[e]) * wv[2][2 * e];
;         ov[2 * e + 1] = bv[2 * e + 1] + hi_bf(qp[e]) * wv[0][2 * e + 1] + hi_bf(qc[e]) * wv[1][2 * e + 1] + hi_bf(qn[e]) * wv[2][2 * e + 1];
;       }
;       uint4 o;
;       o.x = pk2(siluf_(oa[0]) * ov[0], siluf_(oa[1]) * ov[1]); o.y = pk2(siluf_(oa[2]) * ov[2], siluf_(oa[3]) * ov[3]);
;       o.z = pk2(siluf_(oa[4]) * ov[4], siluf_(oa[5]) * ov[5]); o.w = pk2(siluf_(oa[6]) * ov[6], siluf_(oa[7]) * ov[7]);
;       *(uint4*)(ACT + (size_t)(t0 + i) * FFNH + f8) = o;
	v_lshlrev_b32_e32 v126, 16, v220
	v_and_b32_e32 v127, 0xffff0000, v220
	v_pk_fma_f32 v[98:99], v[16:17], v[126:127], v[64:65]
	v_pk_fma_f32 v[82:83], v[32:33], v[126:127], v[82:83]
	v_pk_fma_f32 v[114:115], v[48:49], v[126:127], v[114:115]
	v_lshlrev_b32_e32 v128, 16, v221
	v_and_b32_e32 v129, 0xffff0000, v221
	v_pk_fma_f32 v[100:101], v[18:19], v[128:129], v[66:67]
	v_pk_fma_f32 v[84:85], v[34:35], v[128:129], v[84:85]
	v_pk_fma_f32 v[116:117], v[50:51], v[128:129], v[116:117]
	v_lshlrev_b32_e32 v126, 16, v222
	v_and_b32_e32 v127, 0xffff0000, v222
	v_pk_fma_f32 v[102:103], v[12:13], v[126:127], v[60:61]
	v_pk_fma_f32 v[86:87], v[28:29], v[126:127], v[86:87]
	v_pk_fma_f32 v[118:119], v[44:45], v[126:127], v[118:119]
	v_lshlrev_b32_e32 v128, 16, v223
	v_and_b32_e32 v129, 0xffff0000, v223
	v_pk_fma_f32 v[104:105], v[14:15], v[128:129], v[62:63]
	v_pk_fma_f32 v[88:89], v[30:31], v[128:129], v[88:89]
	v_pk_fma_f32 v[120:121], v[46:47], v[128:129], v[120:121]
	global_load_dwordx4 v[216:219], v[72:73], off nt
	v_lshl_add_u64 v[72:73], v[72:73], 0, s[10:11]
	global_load_dwordx4 v[220:223], v[72:73], off nt
	v_lshl_add_u64 v[72:73], v[72:73], 0, s[10:11]
	v_mul_f32_e32 v122, 0xbfb8aa3b, v106
	v_mul_f32_e32 v123, 0xbfb8aa3b, v107
	v_mul_f32_e32 v124, 0xbfb8aa3b, v108
	v_mul_f32_e32 v125, 0xbfb8aa3b, v109
	v_mul_f32_e32 v126, 0xbfb8aa3b, v110
	v_mul_f32_e32 v127, 0xbfb8aa3b, v111
	v_mul_f32_e32 v128, 0xbfb8aa3b, v112
	v_mul_f32_e32 v129, 0xbfb8aa3b, v113
	v_exp_f32_e32 v122, v122
	v_exp_f32_e32 v123, v123
	v_exp_f32_e32 v124, v124
	v_exp_f32_e32 v125, v125
	v_exp_f32_e32 v126, v126
	v_exp_f32_e32 v127, v127
	v_exp_f32_e32 v128, v128
	v_exp_f32_e32 v129, v129
	v_add_f32_e32 v122, 1.0, v122
	v_add_f32_e32 v123, 1.0, v123
	v_add_f32_e32 v124, 1.0, v124
	v_add_f32_e32 v125, 1.0, v125
	v_add_f32_e32 v126, 1.0, v126
	v_add_f32_e32 v127, 1.0, v127
	v_add_f32_e32 v128, 1.0, v128
	v_add_f32_e32 v129, 1.0, v129
	v_rcp_f32_e32 v122, v122
	v_rcp_f32_e32 v123, v123
	v_rcp_f32_e32 v124, v124
	v_rcp_f32_e32 v125, v125
	v_rcp_f32_e32 v126, v126
	v_rcp_f32_e32 v127, v127
	v_rcp_f32_e32 v128, v128
	v_rcp_f32_e32 v129, v129
	v_pk_mul_f32 v[106:107], v[106:107], v[122:123]
	v_pk_mul_f32 v[108:109], v[108:109], v[124:125]
	v_pk_mul_f32 v[110:111], v[110:111], v[126:127]
	v_pk_mul_f32 v[112:113], v[112:113], v[128:129]
	v_pk_mul_f32 v[106:107], v[114:115], v[106:107]
	v_pk_mul_f32 v[108:109], v[116:117], v[108:109]
	v_pk_mul_f32 v[110:111], v[118:119], v[110:111]
	v_pk_mul_f32 v[112:113], v[120:121], v[112:113]
	v_cvt_pk_bf16_f32 v138, v106, v107
	v_cvt_pk_bf16_f32 v139, v108, v109
	v_cvt_pk_bf16_f32 v140, v110, v111
	v_cvt_pk_bf16_f32 v141, v112, v113
	global_store_dwordx4 v[70:71], v[138:141], off
	v_lshl_add_u64 v[70:71], v[70:71], 0, s[10:11]
	v_lshlrev_b32_e32 v126, 16, v224
	v_and_b32_e32 v127, 0xffff0000, v224
	v_pk_fma_f32 v[106:107], v[8:9], v[126:127], v[56:57]
	v_pk_fma_f32 v[90:91], v[24:25], v[126:127], v[90:91]
	v_pk_fma_f32 v[74:75], v[40:41], v[126:127], v[74:75]
	v_lshlrev_b32_e32 v128, 16, v225
	v_and_b32_e32 v129, 0xffff0000, v225
	v_pk_fma_f32 v[108:109], v[10:11], v[128:129], v[58:59]
	v_pk_fma_f32 v[92:93], v[26:27], v[128:129], v[92:93]
	v_pk_fma_f32 v[76:77], v[42:43], v[128:129], v[76:77]
	v_lshlrev_b32_e32 v126, 16, v226
	v_and_b32_e32 v127, 0xffff0000, v226
	v_pk_fma_f32 v[110:111], v[4:5], v[126:127], v[52:53]
	v_pk_fma_f32 v[94:95], v[20:21], v[126:127], v[94:95]
	v_pk_fma_f32 v[78:79], v[36:37], v[126:127], v[78:79]
	v_lshlrev_b32_e32 v128, 16, v227
	v_and_b32_e32 v129, 0xffff0000, v227
	v_pk_fma_f32 v[112:113], v[6:7], v[128:129], v[54:55]
	v_pk_fma_f32 v[96:97], v[22:23], v[128:129], v[96:97]
	v_pk_fma_f32 v[80:81], v[38:39], v[128:129], v[80:81]
	v_lshlrev_b32_e32 v126, 16, v228
	v_and_b32_e32 v127, 0xffff0000, v228
	v_pk_fma_f32 v[114:115], v[16:17], v[126:127], v[64:65]
	v_pk_fma_f32 v[98:99], v[32:33], v[126:127], v[98:99]
	v_pk_fma_f32 v[82:83], v[48:49], v[126:127], v[82:83]
	v_lshlrev_b32_e32 v128, 16, v229
	v_and_b32_e32 v129, 0xffff0000, v229
	v_pk_fma_f32 v[116:117], v[18:19], v[128:129], v[66:67]
	v_pk_fma_f32 v[100:101], v[34:35], v[128:129], v[100:101]
	v_pk_fma_f32 v[84:85], v[50:51], v[128:129], v[84:85]
	v_lshlrev_b32_e32 v126, 16, v230
	v_and_b32_e32 v127, 0xffff0000, v230
	v_pk_fma_f32 v[118:119], v[12:13], v[126:127], v[60:61]
	v_pk_fma_f32 v[102:103], v[28:29], v[126:127], v[102:103]
	v_pk_fma_f32 v[86:87], v[44:45], v[126:127], v[86:87]
	v_lshlrev_b32_e32 v128, 16, v231
	v_and_b32_e32 v129, 0xffff0000, v231
	v_pk_fma_f32 v[120:121], v[14:15], v[128:129], v[62:63]
	v_pk_fma_f32 v[104:105], v[30:31], v[128:129], v[104:105]
	v_pk_fma_f32 v[88:89], v[46:47], v[128:129], v[88:89]
	v_mul_f32_e32 v122, 0xbfb8aa3b, v74
	v_mul_f32_e32 v123, 0xbfb8aa3b, v75
	v_mul_f32_e32 v124, 0xbfb8aa3b, v76
	v_mul_f32_e32 v125, 0xbfb8aa3b, v77
	v_mul_f32_e32 v126, 0xbfb8aa3b, v78
	v_mul_f32_e32 v127, 0xbfb8aa3b, v79
	v_mul_f32_e32 v128, 0xbfb8aa3b, v80
	v_mul_f32_e32 v129, 0xbfb8aa3b, v81
	v_exp_f32_e32 v122, v122
	v_exp_f32_e32 v123, v123
	v_exp_f32_e32 v124, v124
	v_exp_f32_e32 v125, v125
	v_exp_f32_e32 v126, v126
	v_exp_f32_e32 v127, v127
	v_exp_f32_e32 v128, v128
	v_exp_f32_e32 v129, v129
	v_add_f32_e32 v122, 1.0, v122
	v_add_f32_e32 v123, 1.0, v123
	v_add_f32_e32 v124, 1.0, v124
	v_add_f32_e32 v125, 1.0, v125
	v_add_f32_e32 v126, 1.0, v126
	v_add_f32_e32 v127, 1.0, v127
	v_add_f32_e32 v128, 1.0, v128
	v_add_f32_e32 v129, 1.0, v129
	v_rcp_f32_e32 v122, v122
	v_rcp_f32_e32 v123, v123
	v_rcp_f32_e32 v124, v124
	v_rcp_f32_e32 v125, v125
	v_rcp_f32_e32 v126, v126
	v_rcp_f32_e32 v127, v127
	v_rcp_f32_e32 v128, v128
	v_rcp_f32_e32 v129, v129
; __device__ void conv_phase(int swave, const Params& p, int layer, int h) {
;     ...
;   for (int it = bidx * 512 + tidx; it < (TOK / 16) * NG; it += gridDim.x * 512) {
;     const int f8 = (it % NG) * 8, t0 = (it / NG) * 16, s0 = t0 & (SEQ - 1);
;     const int fa = FC0 + f8, fv = FFN + FC0 + f8;
;     float wa[3][8], wv[3][8], ba[8], bv[8];
; #pragma unroll
;     for (int tap = 0; tap < 3; ++tap) {
;       const float4 a0 = *(const float4*)(cw + tap * 5632 + fa), a1 = *(const float4*)(cw + tap * 5632 + fa + 4);
;       const float4 v0 = *(const float4*)(cw + tap * 5632 + fv), v1 = *(const float4*)(cw + tap * 5632 + fv + 4);
;       wa[tap][0] = a0.x; wa[tap][1] = a0.y; wa[tap][2] = a0.z; wa[tap][3] = a0.w; wa[tap][4] = a1.x; wa[tap][5] = a1.y; wa[tap][6] = a1.z; wa[tap][7] = a1.w;
;       wv[tap][0] = v0.x; wv[tap][1] = v0.y; wv[tap][2] = v0.z; wv[tap][3] = v0.w; wv[tap][4] = v1.x; wv[tap][5] = v1.y; wv[tap][6] = v1.z; wv[tap][7] = v1.w;
;     }
;     {
;       const float4 a0 = *(const float4*)(cb + fa), a1 = *(const float4*)(cb + fa + 4), v0 = *(const float4*)(cb + fv), v1 = *(const float4*)(cb + fv + 4);
;       ba[0] = a0.x; ba[1] = a0.y; ba[2] = a0.z; ba[3] = a0.w; ba[4] = a1.x; ba[5] = a1.y; ba[6] = a1.z; ba[7] = a1.w;
;       bv[0] = v0.x; bv[1] = v0.y; bv[2] = v0.z; bv[3] = v0.w; bv[4] = v1.x; bv[5] = v1.y; bv[6] = v1.z; bv[7] = v1.w;
;     }
;     const bf16_t* base = U + (size_t)t0 * ULD + f8;
;     const uint4 zero4 = make_uint4(0u, 0u, 0u, 0u);
;     uint4 pa = zero4, pv = zero4;
;     if (s0 > 0) { pa = ld_nt16(base - ULD); pv = ld_nt16(base - ULD + FFNH); }
;     uint4 ca = ld_nt16(base), cv = ld_nt16(base + FFNH);
; #pragma unroll 4
;     for (int i = 0; i < 16; ++i) {
;       uint4 na = zero4, nv = zero4;
;       if (s0 + i + 1 < SEQ) { na = ld_nt16(base + (size_t)(i + 1) * ULD); nv = ld_nt16(base + (size_t)(i + 1) * ULD + FFNH); }
;       const unsigned rp[4] = {pa.x, pa.y, pa.z, pa.w}, rc[4] = {ca.x, ca.y, ca.z, ca.w}, rn[4] = {na.x, na.y, na.z, na.w};
;       const unsigned qp[4] = {pv.x, pv.y, pv.z, pv.w}, qc[4] = {cv.x, cv.y, cv.z, cv.w}, qn[4] = {nv.x, nv.y, nv.z, nv.w};
;       float oa[8], ov[8];
; #pragma unroll
;       for (int e = 0; e < 4; ++e) {
;         oa[2 * e] = ba[2 * e] + lo_bf(rp[e]) * wa[0][2 * e] + lo_bf(rc[e]) * wa[1][2 * e] + lo_bf(rn[e]) * wa[2][2 * e];
	v_pk_mul_f32 v[74:75], v[74:75], v[122:123]
	v_pk_mul_f32 v[76:77], v[76:77], v[124:125]
	v_pk_mul_f32 v[78:79], v[78:79], v[126:127]
	v_pk_mul_f32 v[80:81], v[80:81], v[128:129]
	v_pk_mul_f32 v[74:75], v[82:83], v[74:75]
	v_pk_mul_f32 v[76:77], v[84:85], v[76:77]
	v_pk_mul_f32 v[78:79], v[86:87], v[78:79]
	v_pk_mul_f32 v[80:81], v[88:89], v[80:81]
	v_cvt_pk_bf16_f32 v138, v74, v75
	v_cvt_pk_bf16_f32 v139, v76, v77
	v_cvt_pk_bf16_f32 v140, v78, v79
	v_cvt_pk_bf16_f32 v141, v80, v81
	global_store_dwordx4 v[70:71], v[138:141], off
	v_lshl_add_u64 v[70:71], v[70:71], 0, s[10:11]
	v_lshlrev_b32_e32 v126, 16, v232
	v_and_b32_e32 v127, 0xffff0000, v232
	v_pk_fma_f32 v[74:75], v[8:9], v[126:127], v[56:57]
	v_pk_fma_f32 v[106:107], v[24:25], v[126:127], v[106:107]
	v_pk_fma_f32 v[90:91], v[40:41], v[126:127], v[90:91]
	v_lshlrev_b32_e32 v128, 16, v233
	v_and_b32_e32 v129, 0xffff0000, v233
	v_pk_fma_f32 v[76:77], v[10:11], v[128:129], v[58:59]
	v_pk_fma_f32 v[108:109], v[26:27], v[128:129], v[108:109]
	v_pk_fma_f32 v[92:93], v[42:43], v[128:129], v[92:93]
	v_lshlrev_b32_e32 v126, 16, v234
	v_and_b32_e32 v127, 0xffff0000, v234
	v_pk_fma_f32 v[78:79], v[4:5], v[126:127], v[52:53]
	v_pk_fma_f32 v[110:111], v[20:21], v[126:127], v[110:111]
	v_pk_fma_f32 v[94:95], v[36:37], v[126:127], v[94:95]
	v_lshlrev_b32_e32 v128, 16, v235
	v_and_b32_e32 v129, 0xffff0000, v235
	v_pk_fma_f32 v[80:81], v[6:7], v[128:129], v[54:55]
	v_pk_fma_f32 v[112:113], v[22:23], v[128:129], v[112:113]
	v_pk_fma_f32 v[96:97], v[38:39], v[128:129], v[96:97]
	v_lshlrev_b32_e32 v126, 16, v236
	v_and_b32_e32 v127, 0xffff0000, v236
	v_pk_fma_f32 v[82:83], v[16:17], v[126:127], v[64:65]
	v_pk_fma_f32 v[114:115], v[32:33], v[126:127], v[114:115]
	v_pk_fma_f32 v[98:99], v[48:49], v[126:127], v[98:99]
	v_lshlrev_b32_e32 v128, 16, v237
	v_and_b32_e32 v129, 0xffff0000, v237
	v_pk_fma_f32 v[84:85], v[18:19], v[128:129], v[66:67]
	v_pk_fma_f32 v[116:117], v[34:35], v[128:129], v[116:117]
	v_pk_fma_f32 v[100:101], v[50:51], v[128:129], v[100:101]
	v_lshlrev_b32_e32 v126, 16, v238
	v_and_b32_e32 v127, 0xffff0000, v238
	v_pk_fma_f32 v[86:87], v[12:13], v[126:127], v[60:61]
	v_pk_fma_f32 v[118:119], v[28:29], v[126:127], v[118:119]
	v_pk_fma_f32 v[102:103], v[44:45], v[126:127], v[102:103]
	v_lshlrev_b32_e32 v128, 16, v239
	v_and_b32_e32 v129, 0xffff0000, v239
	v_pk_fma_f32 v[88:89], v[14:15], v[128:129], v[62:63]
	v_pk_fma_f32 v[120:121], v[30:31], v[128:129], v[120:121]
	v_pk_fma_f32 v[104:105], v[46:47], v[128:129], v[104:105]
	v_add_u32_e32 v68, s57, v135
	v_mul_hi_u32 v0, v68, v142
	v_mul_lo_u32 v1, v0, s45
	v_sub_u32_e32 v1, v68, v1
	v_add_u32_e32 v2, 1, v0
	v_cmp_le_u32_e32 vcc, s45, v1
	s_nop 1
	v_cndmask_b32_e32 v0, v0, v2, vcc
	v_subrev_u32_e32 v2, s45, v1
	v_cndmask_b32_e32 v1, v1, v2, vcc
	v_add_u32_e32 v2, 1, v0
	v_cmp_le_u32_e32 vcc, s45, v1
	s_nop 1
	v_cndmask_b32_e32 v0, v0, v2, vcc
	v_mul_lo_u32 v1, v0, s45
	v_sub_u32_e32 v1, v68, v1
	v_lshlrev_b32_e32 v1, 4, v1
	v_mul_lo_u32 v2, v0, s24
	v_add_u32_e32 v2, v2, v1
	v_cmp_gt_i32_e32 vcc, s44, v68
	v_lshl_add_u64 v[0:1], s[4:5], 0, v[2:3]
	v_lshl_add_u64 v[0:1], s[14:15], 1, v[0:1]
	v_mov_b32_e32 v2, s4
	v_mov_b32_e32 v68, s5
	v_cndmask_b32_e32 v72, v2, v0, vcc
	v_cndmask_b32_e32 v73, v68, v1, vcc
	v_mul_f32_e32 v122, 0xbfb8aa3b, v90
	v_mul_f32_e32 v123, 0xbfb8aa3b, v91
	v_mul_f32_e32 v124, 0xbfb8aa3b, v92
	v_mul_f32_e32 v125, 0xbfb8aa3b, v93
	v_mul_f32_e32 v126, 0xbfb8aa3b, v94
	v_mul_f32_e32 v127, 0xbfb8aa3b, v95
	v_mul_f32_e32 v128, 0xbfb8aa3b, v96
	v_mul_f32_e32 v129, 0xbfb8aa3b, v97
	v_exp_f32_e32 v122, v122
	v_exp_f32_e32 v123, v123
	v_exp_f32_e32 v124, v124
	v_exp_f32_e32 v125, v125
	v_exp_f32_e32 v126, v126
	v_exp_f32_e32 v127, v127
	v_exp_f32_e32 v128, v128
	v_exp_f32_e32 v129, v129
	v_add_f32_e32 v122, 1.0, v122
	v_add_f32_e32 v123, 1.0, v123
	v_add_f32_e32 v124, 1.0, v124
	v_add_f32_e32 v125, 1.0, v125
	v_add_f32_e32 v126, 1.0, v126
	v_add_f32_e32 v127, 1.0, v127
	v_add_f32_e32 v128, 1.0, v128
	v_add_f32_e32 v129, 1.0, v129
	v_rcp_f32_e32 v122, v122
	v_rcp_f32_e32 v123, v123
	v_rcp_f32_e32 v124, v124
	v_rcp_f32_e32 v125, v125
	v_rcp_f32_e32 v126, v126
	v_rcp_f32_e32 v127, v127
	v_rcp_f32_e32 v128, v128
	v_rcp_f32_e32 v129, v129
	v_pk_mul_f32 v[90:91], v[90:91], v[122:123]
	v_pk_mul_f32 v[92:93], v[92:93], v[124:125]
	v_pk_mul_f32 v[94:95], v[94:95], v[126:127]
	v_pk_mul_f32 v[96:97], v[96:97], v[128:129]
	v_pk_mul_f32 v[90:91], v[98:99], v[90:91]
	v_pk_mul_f32 v[92:93], v[100:101], v[92:93]
	v_pk_mul_f32 v[94:95], v[102:103], v[94:95]
	v_pk_mul_f32 v[96:97], v[104:105], v[96:97]
	v_cvt_pk_bf16_f32 v138, v90, v91
	v_cvt_pk_bf16_f32 v139, v92, v93
	v_cvt_pk_bf16_f32 v140, v94, v95
	v_cvt_pk_bf16_f32 v141, v96, v97
	global_store_dwordx4 v[70:71], v[138:141], off
	v_lshl_add_u64 v[70:71], v[70:71], 0, s[10:11]
	s_waitcnt vmcnt(22)
; __device__ __forceinline__ uint4 ld_nt16(const void* p) { const u32x4_t t = __builtin_nontemporal_load((const u32x4_t*)p); return make_uint4(t[0], t[1], t[2], t[3]); }
; __device__ __forceinline__ unsigned pk2(float lo, float hi) { f32x2_t v = {lo, hi}; bf16x2_t b = __builtin_convertvector(v, bf16x2_t); return __builtin_bit_cast(unsigned, b); }
; __device__ __forceinline__ float lo_bf(unsigned u) { return __uint_as_float(u << 16); }
; __device__ __forceinline__ float hi_bf(unsigned u) { return __uint_as_float(u & 0xffff0000u); }
; __device__ __forceinline__ float siluf_(float x) { return x * __builtin_amdgcn_rcpf(1.f + __expf(-x)); }
; __device__ void conv_phase(int swave, const Params& p, int layer, int h) {
;     ...
;     for (int i = 0; i < 16; ++i) {
;       uint4 na = zero4, nv = zero4;
;       if (s0 + i + 1 < SEQ) { na = ld_nt16(base + (size_t)(i + 1) * ULD); nv = ld_nt16(base + (size_t)(i + 1) * ULD + FFNH); }
;       const unsigned rp[4] = {pa.x, pa.y, pa.z, pa.w}, rc[4] = {ca.x, ca.y, ca.z, ca.w}, rn[4] = {na.x, na.y, na.z, na.w};
;       const unsigned qp[4] = {pv.x, pv.y, pv.z, pv.w}, qc[4] = {cv.x, cv.y, cv.z, cv.w}, qn[4] = {nv.x, nv.y, nv.z, nv.w};
;       float oa[8], ov[8];
; #pragma unroll
;       for (int e = 0; e < 4; ++e) {
;         oa[2 * e] = ba[2 * e] + lo_bf(rp[e]) * wa[0][2 * e] + lo_bf(rc[e]) * wa[1][2 * e] + lo_bf(rn[e]) * wa[2][2 * e];
;         oa[2 * e + 1] = ba[2 * e + 1] + hi_bf(rp[e]) * wa[0][2 * e + 1] + hi_bf(rc[e]) * wa[1][2 * e + 1] + hi_bf(rn[e]) * wa[2][2 * e + 1];
;         ov[2 * e] = bv[2 * e] + lo_bf(qp[e]) * wv[0][2 * e] + lo_bf(qc[e]) * wv[1][2 * e] + lo_bf(qn[e]) * wv[2][2 * e];
;         ov[2 * e + 1] = bv[2 * e + 1] + hi_bf(qp[e]) * wv[0][2 * e + 1] + hi_bf(qc[e]) * wv[1][2 * e + 1] + hi_bf(qn[e]) * wv[2][2 * e + 1];
;       }
;       uint4 o;
;       o.x = pk2(siluf_(oa[0]) * ov[0], siluf_(oa[1]) * ov[1]); o.y = pk2(siluf_(oa[2]) * ov[2], siluf_(oa[3]) * ov[3]);
;       o.z = pk2(siluf_(oa[4]) * ov[4], siluf_(oa[5]) * ov[5]); o.w = pk2(siluf_(oa[6]) * ov[6], siluf_(oa[7]) * ov[7]);
;       *(uint4*)(ACT + (size_t)(t0 + i) * FFNH + f8) = o;
	v_lshlrev_b32_e32 v126, 16, v160
	v_and_b32_e32 v127, 0xffff0000, v160
	v_pk_fma_f32 v[90:91], v[8:9], v[126:127], v[56:57]
	v_pk_fma_f32 v[74:75], v[24:25], v[126:127], v[74:75]
	v_pk_fma_f32 v[106:107], v[40:41], v[126:127], v[106:107]
	v_lshlrev_b32_e32 v128, 16, v161
	v_and_b32_e32 v129, 0xffff0000, v161
	v_pk_fma_f32 v[92:93], v[10:11], v[128:129], v[58:59]
	v_pk_fma_f32 v[76:77], v[26:27], v[128:129], v[76:77]
	v_pk_fma_f32 v[108:109], v[42:43], v[128:129], v[108:109]
	v_lshlrev_b32_e32 v126, 16, v162
	v_and_b32_e32 v127, 0xffff0000, v162
	v_pk_fma_f32 v[94:95], v[4:5], v[126:127], v[52:53]
	v_pk_fma_f32 v[78:79], v[20:21], v[126:127], v[78:79]
	v_pk_fma_f32 v[110:111], v[36:37], v[126:127], v[110:111]
	v_lshlrev_b32_e32 v128, 16, v163
	v_and_b32_e32 v129, 0xffff0000, v163
	v_pk_fma_f32 v[96:97], v[6:7], v[128:129], v[54:55]
	v_pk_fma_f32 v[80:81], v[22:23], v[128:129], v[80:81]
	v_pk_fma_f32 v[112:113], v[38:39], v[128:129], v[112:113]
	v_lshlrev_b32_e32 v126, 16, v164
	v_and_b32_e32 v127, 0xffff0000, v164
	v_pk_fma_f32 v[98:99], v[16:17], v[126:127], v[64:65]
	v_pk_fma_f32 v[82:83], v[32:33], v[126:127], v[82:83]
	v_pk_fma_f32 v[114:115], v[48:49], v[126:127], v[114:115]
	v_lshlrev_b32_e32 v128, 16, v165
	v_and_b32_e32 v129, 0xffff0000, v165
	v_pk_fma_f32 v[100:101], v[18:19], v[128:129], v[66:67]
	v_pk_fma_f32 v[84:85], v[34:35], v[128:129], v[84:85]
	v_pk_fma_f32 v[116:117], v[50:51], v[128:129], v[116:117]
	v_lshlrev_b32_e32 v126, 16, v166
	v_and_b32_e32 v127, 0xffff0000, v166
	v_pk_fma_f32 v[102:103], v[12:13], v[126:127], v[60:61]
	v_pk_fma_f32 v[86:87], v[28:29], v[126:127], v[86:87]
	v_pk_fma_f32 v[118:119], v[44:45], v[126:127], v[118:119]
	v_lshlrev_b32_e32 v128, 16, v167
	v_and_b32_e32 v129, 0xffff0000, v167
	v_pk_fma_f32 v[104:105], v[14:15], v[128:129], v[62:63]
	v_pk_fma_f32 v[88:89], v[30:31], v[128:129], v[88:89]
	v_pk_fma_f32 v[120:121], v[46:47], v[128:129], v[120:121]
	global_load_dwordx4 v[160:163], v[72:73], off nt
	v_lshl_add_u64 v[72:73], v[72:73], 0, s[10:11]
	global_load_dwordx4 v[164:167], v[72:73], off nt
	v_lshl_add_u64 v[72:73], v[72:73], 0, s[10:11]
	v_mul_f32_e32 v122, 0xbfb8aa3b, v106
	v_mul_f32_e32 v123, 0xbfb8aa3b, v107
	v_mul_f32_e32 v124, 0xbfb8aa3b, v108
	v_mul_f32_e32 v125, 0xbfb8aa3b, v109
	v_mul_f32_e32 v126, 0xbfb8aa3b, v110
	v_mul_f32_e32 v127, 0xbfb8aa3b, v111
	v_mul_f32_e32 v128, 0xbfb8aa3b, v112
	v_mul_f32_e32 v129, 0xbfb8aa3b, v113
	v_exp_f32_e32 v122, v122
	v_exp_f32_e32 v123, v123
	v_exp_f32_e32 v124, v124
	v_exp_f32_e32 v125, v125
	v_exp_f32_e32 v126, v126
	v_exp_f32_e32 v127, v127
	v_exp_f32_e32 v128, v128
	v_exp_f32_e32 v129, v129
	v_add_f32_e32 v122, 1.0, v122
	v_add_f32_e32 v123, 1.0, v123
	v_add_f32_e32 v124, 1.0, v124
	v_add_f32_e32 v125, 1.0, v125
	v_add_f32_e32 v126, 1.0, v126
	v_add_f32_e32 v127, 1.0, v127
	v_add_f32_e32 v128, 1.0, v128
	v_add_f32_e32 v129, 1.0, v129
	v_rcp_f32_e32 v122, v122
	v_rcp_f32_e32 v123, v123
	v_rcp_f32_e32 v124, v124
	v_rcp_f32_e32 v125, v125
	v_rcp_f32_e32 v126, v126
	v_rcp_f32_e32 v127, v127
	v_rcp_f32_e32 v128, v128
	v_rcp_f32_e32 v129, v129
	v_pk_mul_f32 v[106:107], v[106:107], v[122:123]
	v_pk_mul_f32 v[108:109], v[108:109], v[124:125]
	v_pk_mul_f32 v[110:111], v[110:111], v[126:127]
	v_pk_mul_f32 v[112:113], v[112:113], v[128:129]
	v_pk_mul_f32 v[106:107], v[114:115], v[106:107]
	v_pk_mul_f32 v[108:109], v[116:117], v[108:109]
	v_pk_mul_f32 v[110:111], v[118:119], v[110:111]
	v_pk_mul_f32 v[112:113], v[120:121], v[112:113]
	v_cvt_pk_bf16_f32 v138, v106, v107
	v_cvt_pk_bf16_f32 v139, v108, v109
	v_cvt_pk_bf16_f32 v140, v110, v111
	v_cvt_pk_bf16_f32 v141, v112, v113
	global_store_dwordx4 v[70:71], v[138:141], off
	v_lshl_add_u64 v[70:71], v[70:71], 0, s[10:11]
	s_waitcnt vmcnt(23)
	v_lshlrev_b32_e32 v126, 16, v168
	v_and_b32_e32 v127, 0xffff0000, v168
	v_pk_fma_f32 v[106:107], v[8:9], v[126:127], v[56:57]
	v_pk_fma_f32 v[90:91], v[24:25], v[126:127], v[90:91]
	v_pk_fma_f32 v[74:75], v[40:41], v[126:127], v[74:75]
	v_lshlrev_b32_e32 v128, 16, v169
	v_and_b32_e32 v129, 0xffff0000, v169
	v_pk_fma_f32 v[108:109], v[10:11], v[128:129], v[58:59]
	v_pk_fma_f32 v[92:93], v[26:27], v[128:129], v[92:93]
	v_pk_fma_f32 v[76:77], v[42:43], v[128:129], v[76:77]
	v_lshlrev_b32_e32 v126, 16, v170
	v_and_b32_e32 v127, 0xffff0000, v170
	v_pk_fma_f32 v[110:111], v[4:5], v[126:127], v[52:53]
	v_pk_fma_f32 v[94:95], v[20:21], v[126:127], v[94:95]
	v_pk_fma_f32 v[78:79], v[36:37], v[126:127], v[78:79]
	v_lshlrev_b32_e32 v128, 16, v171
	v_and_b32_e32 v129, 0xffff0000, v171
	v_pk_fma_f32 v[112:113], v[6:7], v[128:129], v[54:55]
	v_pk_fma_f32 v[96:97], v[22:23], v[128:129], v[96:97]
	v_pk_fma_f32 v[80:81], v[38:39], v[128:129], v[80:81]
	v_lshlrev_b32_e32 v126, 16, v172
	v_and_b32_e32 v127, 0xffff0000, v172
	v_pk_fma_f32 v[114:115], v[16:17], v[126:127], v[64:65]
	v_pk_fma_f32 v[98:99], v[32:33], v[126:127], v[98:99]
	v_pk_fma_f32 v[82:83], v[48:49], v[126:127], v[82:83]
	v_lshlrev_b32_e32 v128, 16, v173
	v_and_b32_e32 v129, 0xffff0000, v173
	v_pk_fma_f32 v[116:117], v[18:19], v[128:129], v[66:67]
	v_pk_fma_f32 v[100:101], v[34:35], v[128:129], v[100:101]
	v_pk_fma_f32 v[84:85], v[50:51], v[128:129], v[84:85]
	v_lshlrev_b32_e32 v126, 16, v174
	v_and_b32_e32 v127, 0xffff0000, v174
	v_pk_fma_f32 v[118:119], v[12:13], v[126:127], v[60:61]
	v_pk_fma_f32 v[102:103], v[28:29], v[126:127], v[102:103]
	v_pk_fma_f32 v[86:87], v[44:45], v[126:127], v[86:87]
	v_lshlrev_b32_e32 v128, 16, v175
	v_and_b32_e32 v129, 0xffff0000, v175
	v_pk_fma_f32 v[120:121], v[14:15], v[128:129], v[62:63]
	v_pk_fma_f32 v[104:105], v[30:31], v[128:129], v[104:105]
	v_pk_fma_f32 v[88:89], v[46:47], v[128:129], v[88:89]
; __device__ __forceinline__ uint4 ld_nt16(const void* p) { const u32x4_t t = __builtin_nontemporal_load((const u32x4_t*)p); return make_uint4(t[0], t[1], t[2], t[3]); }
; __device__ __forceinline__ unsigned pk2(float lo, float hi) { f32x2_t v = {lo, hi}; bf16x2_t b = __builtin_convertvector(v, bf16x2_t); return __builtin_bit_cast(unsigned, b); }
; __device__ __forceinline__ float lo_bf(unsigned u) { return __uint_as_float(u << 16); }
; __device__ __forceinline__ float hi_bf(unsigned u) { return __uint_as_float(u & 0xffff0000u); }
; __device__ __forceinline__ float siluf_(float x) { return x * __builtin_amdgcn_rcpf(1.f + __expf(-x)); }
; __device__ void conv_phase(int swave, const Params& p, int layer, int h) {
;     ...
;     for (int i = 0; i < 16; ++i) {
;       uint4 na = zero4, nv = zero4;
;       if (s0 + i + 1 < SEQ) { na = ld_nt16(base + (size_t)(i + 1) * ULD); nv = ld_nt16(base + (size_t)(i + 1) * ULD + FFNH); }
;       const unsigned rp[4] = {pa.x, pa.y, pa.z, pa.w}, rc[4] = {ca.x, ca.y, ca.z, ca.w}, rn[4] = {na.x, na.y, na.z, na.w};
;       const unsigned qp[4] = {pv.x, pv.y, pv.z, pv.w}, qc[4] = {cv.x, cv.y, cv.z, cv.w}, qn[4] = {nv.x, nv.y, nv.z, nv.w};
;       float oa[8], ov[8];
; #pragma unroll
;       for (int e = 0; e < 4; ++e) {
;         oa[2 * e] = ba[2 * e] + lo_bf(rp[e]) * wa[0][2 * e] + lo_bf(rc[e]) * wa[1][2 * e] + lo_bf(rn[e]) * wa[2][2 * e];
;         oa[2 * e + 1] = ba[2 * e + 1] + hi_bf(rp[e]) * wa[0][2 * e + 1] + hi_bf(rc[e]) * wa[1][2 * e + 1] + hi_bf(rn[e]) * wa[2][2 * e + 1];
;         ov[2 * e] = bv[2 * e] + lo_bf(qp[e]) * wv[0][2 * e] + lo_bf(qc[e]) * wv[1][2 * e] + lo_bf(qn[e]) * wv[2][2 * e];
;         ov[2 * e + 1] = bv[2 * e + 1] + hi_bf(qp[e]) * wv[0][2 * e + 1] + hi_bf(qc[e]) * wv[1][2 * e + 1] + hi_bf(qn[e]) * wv[2][2 * e + 1];
;       }
;       uint4 o;
;       o.x = pk2(siluf_(oa[0]) * ov[0], siluf_(oa[1]) * ov[1]); o.y = pk2(siluf_(oa[2]) * ov[2], siluf_(oa[3]) * ov[3]);
;       o.z = pk2(siluf_(oa[4]) * ov[4], siluf_(oa[5]) * ov[5]); o.w = pk2(siluf_(oa[6]) * ov[6], siluf_(oa[7]) * ov[7]);
;       *(uint4*)(ACT + (size_t)(t0 + i) * FFNH + f8) = o;
	global_load_dwordx4 v[168:171], v[72:73], off nt
	v_lshl_add_u64 v[72:73], v[72:73], 0, s[10:11]
	global_load_dwordx4 v[172:175], v[72:73], off nt
	v_lshl_add_u64 v[72:73], v[72:73], 0, s[10:11]
	v_mul_f32_e32 v122, 0xbfb8aa3b, v74
	v_mul_f32_e32 v123, 0xbfb8aa3b, v75
	v_mul_f32_e32 v124, 0xbfb8aa3b, v76
	v_mul_f32_e32 v125, 0xbfb8aa3b, v77
	v_mul_f32_e32 v126, 0xbfb8aa3b, v78
	v_mul_f32_e32 v127, 0xbfb8aa3b, v79
	v_mul_f32_e32 v128, 0xbfb8aa3b, v80
	v_mul_f32_e32 v129, 0xbfb8aa3b, v81
	v_exp_f32_e32 v122, v122
	v_exp_f32_e32 v123, v123
	v_exp_f32_e32 v124, v124
	v_exp_f32_e32 v125, v125
	v_exp_f32_e32 v126, v126
	v_exp_f32_e32 v127, v127
	v_exp_f32_e32 v128, v128
	v_exp_f32_e32 v129, v129
	v_add_f32_e32 v122, 1.0, v122
	v_add_f32_e32 v123, 1.0, v123
	v_add_f32_e32 v124, 1.0, v124
	v_add_f32_e32 v125, 1.0, v125
	v_add_f32_e32 v126, 1.0, v126
	v_add_f32_e32 v127, 1.0, v127
	v_add_f32_e32 v128, 1.0, v128
	v_add_f32_e32 v129, 1.0, v129
	v_rcp_f32_e32 v122, v122
	v_rcp_f32_e32 v123, v123
	v_rcp_f32_e32 v124, v124
	v_rcp_f32_e32 v125, v125
	v_rcp_f32_e32 v126, v126
	v_rcp_f32_e32 v127, v127
	v_rcp_f32_e32 v128, v128
	v_rcp_f32_e32 v129, v129
	v_pk_mul_f32 v[74:75], v[74:75], v[122:123]
	v_pk_mul_f32 v[76:77], v[76:77], v[124:125]
	v_pk_mul_f32 v[78:79], v[78:79], v[126:127]
	v_pk_mul_f32 v[80:81], v[80:81], v[128:129]
	v_pk_mul_f32 v[74:75], v[82:83], v[74:75]
	v_pk_mul_f32 v[76:77], v[84:85], v[76:77]
	v_pk_mul_f32 v[78:79], v[86:87], v[78:79]
	v_pk_mul_f32 v[80:81], v[88:89], v[80:81]
	v_cvt_pk_bf16_f32 v138, v74, v75
	v_cvt_pk_bf16_f32 v139, v76, v77
	v_cvt_pk_bf16_f32 v140, v78, v79
	v_cvt_pk_bf16_f32 v141, v80, v81
	global_store_dwordx4 v[70:71], v[138:141], off
	v_lshl_add_u64 v[70:71], v[70:71], 0, s[10:11]
	s_waitcnt vmcnt(24)
	v_lshlrev_b32_e32 v126, 16, v176
	v_and_b32_e32 v127, 0xffff0000, v176
	v_pk_fma_f32 v[74:75], v[8:9], v[126:127], v[56:57]
	v_pk_fma_f32 v[106:107], v[24:25], v[126:127], v[106:107]
	v_pk_fma_f32 v[90:91], v[40:41], v[126:127], v[90:91]
	v_lshlrev_b32_e32 v128, 16, v177
	v_and_b32_e32 v129, 0xffff0000, v177
	v_pk_fma_f32 v[76:77], v[10:11], v[128:129], v[58:59]
	v_pk_fma_f32 v[108:109], v[26:27], v[128:129], v[108:109]
	v_pk_fma_f32 v[92:93], v[42:43], v[128:129], v[92:93]
	v_lshlrev_b32_e32 v126, 16, v178
	v_and_b32_e32 v127, 0xffff0000, v178
	v_pk_fma_f32 v[78:79], v[4:5], v[126:127], v[52:53]
	v_pk_fma_f32 v[110:111], v[20:21], v[126:127], v[110:111]
	v_pk_fma_f32 v[94:95], v[36:37], v[126:127], v[94:95]
	v_lshlrev_b32_e32 v128, 16, v179
	v_and_b32_e32 v129, 0xffff0000, v179
	v_pk_fma_f32 v[80:81], v[6:7], v[128:129], v[54:55]
	v_pk_fma_f32 v[112:113], v[22:23], v[128:129], v[112:113]
	v_pk_fma_f32 v[96:97], v[38:39], v[128:129], v[96:97]
	v_lshlrev_b32_e32 v126, 16, v180
	v_and_b32_e32 v127, 0xffff0000, v180
	v_pk_fma_f32 v[82:83], v[16:17], v[126:127], v[64:65]
	v_pk_fma_f32 v[114:115], v[32:33], v[126:127], v[114:115]
	v_pk_fma_f32 v[98:99], v[48:49], v[126:127], v[98:99]
	v_lshlrev_b32_e32 v128, 16, v181
	v_and_b32_e32 v129, 0xffff0000, v181
	v_pk_fma_f32 v[84:85], v[18:19], v[128:129], v[66:67]
	v_pk_fma_f32 v[116:117], v[34:35], v[128:129], v[116:117]
	v_pk_fma_f32 v[100:101], v[50:51], v[128:129], v[100:101]
	v_lshlrev_b32_e32 v126, 16, v182
	v_and_b32_e32 v127, 0xffff0000, v182
	v_pk_fma_f32 v[86:87], v[12:13], v[126:127], v[60:61]
	v_pk_fma_f32 v[118:119], v[28:29], v[126:127], v[118:119]
	v_pk_fma_f32 v[102:103], v[44:45], v[126:127], v[102:103]
	v_lshlrev_b32_e32 v128, 16, v183
	v_and_b32_e32 v129, 0xffff0000, v183
	v_pk_fma_f32 v[88:89], v[14:15], v[128:129], v[62:63]
	v_pk_fma_f32 v[120:121], v[30:31], v[128:129], v[120:121]
	v_pk_fma_f32 v[104:105], v[46:47], v[128:129], v[104:105]
	global_load_dwordx4 v[176:179], v[72:73], off nt
	v_lshl_add_u64 v[72:73], v[72:73], 0, s[10:11]
	global_load_dwordx4 v[180:183], v[72:73], off nt
	v_lshl_add_u64 v[72:73], v[72:73], 0, s[10:11]
	v_mul_f32_e32 v122, 0xbfb8aa3b, v90
	v_mul_f32_e32 v123, 0xbfb8aa3b, v91
	v_mul_f32_e32 v124, 0xbfb8aa3b, v92
	v_mul_f32_e32 v125, 0xbfb8aa3b, v93
	v_mul_f32_e32 v126, 0xbfb8aa3b, v94
	v_mul_f32_e32 v127, 0xbfb8aa3b, v95
	v_mul_f32_e32 v128, 0xbfb8aa3b, v96
	v_mul_f32_e32 v129, 0xbfb8aa3b, v97
	v_exp_f32_e32 v122, v122
	v_exp_f32_e32 v123, v123
	v_exp_f32_e32 v124, v124
	v_exp_f32_e32 v125, v125
	v_exp_f32_e32 v126, v126
	v_exp_f32_e32 v127, v127
	v_exp_f32_e32 v128, v128
	v_exp_f32_e32 v129, v129
	v_add_f32_e32 v122, 1.0, v122
	v_add_f32_e32 v123, 1.0, v123
	v_add_f32_e32 v124, 1.0, v124
	v_add_f32_e32 v125, 1.0, v125
	v_add_f32_e32 v126, 1.0, v126
	v_add_f32_e32 v127, 1.0, v127
	v_add_f32_e32 v128, 1.0, v128
	v_add_f32_e32 v129, 1.0, v129
	v_rcp_f32_e32 v122, v122
	v_rcp_f32_e32 v123, v123
	v_rcp_f32_e32 v124, v124
	v_rcp_f32_e32 v125, v125
	v_rcp_f32_e32 v126, v126
	v_rcp_f32_e32 v127, v127
	v_rcp_f32_e32 v128, v128
	v_rcp_f32_e32 v129, v129
	v_pk_mul_f32 v[90:91], v[90:91], v[122:123]
	v_pk_mul_f32 v[92:93], v[92:93], v[124:125]
	v_pk_mul_f32 v[94:95], v[94:95], v[126:127]
	v_pk_mul_f32 v[96:97], v[96:97], v[128:129]
	v_pk_mul_f32 v[90:91], v[98:99], v[90:91]
	v_pk_mul_f32 v[92:93], v[100:101], v[92:93]
	v_pk_mul_f32 v[94:95], v[102:103], v[94:95]
	v_pk_mul_f32 v[96:97], v[104:105], v[96:97]
	v_cvt_pk_bf16_f32 v138, v90, v91
	v_cvt_pk_bf16_f32 v139, v92, v93
	v_cvt_pk_bf16_f32 v140, v94, v95
	v_cvt_pk_bf16_f32 v141, v96, v97
	global_store_dwordx4 v[70:71], v[138:141], off
	v_lshl_add_u64 v[70:71], v[70:71], 0, s[10:11]
	s_waitcnt vmcnt(24)
; __device__ __forceinline__ uint4 ld_nt16(const void* p) { const u32x4_t t = __builtin_nontemporal_load((const u32x4_t*)p); return make_uint4(t[0], t[1], t[2], t[3]); }
; __device__ __forceinline__ unsigned pk2(float lo, float hi) { f32x2_t v = {lo, hi}; bf16x2_t b = __builtin_convertvector(v, bf16x2_t); return __builtin_bit_cast(unsigned, b); }
; __device__ __forceinline__ float lo_bf(unsigned u) { return __uint_as_float(u << 16); }
; __device__ __forceinline__ float hi_bf(unsigned u) { return __uint_as_float(u & 0xffff0000u); }
; __device__ __forceinline__ float siluf_(float x) { return x * __builtin_amdgcn_rcpf(1.f + __expf(-x)); }
; __device__ void conv_phase(int swave, const Params& p, int layer, int h) {
;     ...
;     for (int i = 0; i < 16; ++i) {
;       uint4 na = zero4, nv = zero4;
;       if (s0 + i + 1 < SEQ) { na = ld_nt16(base + (size_t)(i + 1) * ULD); nv = ld_nt16(base + (size_t)(i + 1) * ULD + FFNH); }
;       const unsigned rp[4] = {pa.x, pa.y, pa.z, pa.w}, rc[4] = {ca.x, ca.y, ca.z, ca.w}, rn[4] = {na.x, na.y, na.z, na.w};
;       const unsigned qp[4] = {pv.x, pv.y, pv.z, pv.w}, qc[4] = {cv.x, cv.y, cv.z, cv.w}, qn[4] = {nv.x, nv.y, nv.z, nv.w};
;       float oa[8], ov[8];
; #pragma unroll
;       for (int e = 0; e < 4; ++e) {
;         oa[2 * e] = ba[2 * e] + lo_bf(rp[e]) * wa[0][2 * e] + lo_bf(rc[e]) * wa[1][2 * e] + lo_bf(rn[e]) * wa[2][2 * e];
;         oa[2 * e + 1] = ba[2 * e + 1] + hi_bf(rp[e]) * wa[0][2 * e + 1] + hi_bf(rc[e]) * wa[1][2 * e + 1] + hi_bf(rn[e]) * wa[2][2 * e + 1];
;         ov[2 * e] = bv[2 * e] + lo_bf(qp[e]) * wv[0][2 * e] + lo_bf(qc[e]) * wv[1][2 * e] + lo_bf(qn[e]) * wv[2][2 * e];
;         ov[2 * e + 1] = bv[2 * e + 1] + hi_bf(qp[e]) * wv[0][2 * e + 1] + hi_bf(qc[e]) * wv[1][2 * e + 1] + hi_bf(qn[e]) * wv[2][2 * e + 1];
;       }
;       uint4 o;
;       o.x = pk2(siluf_(oa[0]) * ov[0], siluf_(oa[1]) * ov[1]); o.y = pk2(siluf_(oa[2]) * ov[2], siluf_(oa[3]) * ov[3]);
;       o.z = pk2(siluf_(oa[4]) * ov[4], siluf_(oa[5]) * ov[5]); o.w = pk2(siluf_(oa[6]) * ov[6], siluf_(oa[7]) * ov[7]);
;       *(uint4*)(ACT + (size_t)(t0 + i) * FFNH + f8) = o;
	v_lshlrev_b32_e32 v126, 16, v184
	v_and_b32_e32 v127, 0xffff0000, v184
	v_pk_fma_f32 v[90:91], v[8:9], v[126:127], v[56:57]
	v_pk_fma_f32 v[74:75], v[24:25], v[126:127], v[74:75]
	v_pk_fma_f32 v[106:107], v[40:41], v[126:127], v[106:107]
	v_lshlrev_b32_e32 v128, 16, v185
	v_and_b32_e32 v129, 0xffff0000, v185
	v_pk_fma_f32 v[92:93], v[10:11], v[128:129], v[58:59]
	v_pk_fma_f32 v[76:77], v[26:27], v[128:129], v[76:77]
	v_pk_fma_f32 v[108:109], v[42:43], v[128:129], v[108:109]
	v_lshlrev_b32_e32 v126, 16, v186
	v_and_b32_e32 v127, 0xffff0000, v186
	v_pk_fma_f32 v[94:95], v[4:5], v[126:127], v[52:53]
	v_pk_fma_f32 v[78:79], v[20:21], v[126:127], v[78:79]
	v_pk_fma_f32 v[110:111], v[36:37], v[126:127], v[110:111]
	v_lshlrev_b32_e32 v128, 16, v187
	v_and_b32_e32 v129, 0xffff0000, v187
	v_pk_fma_f32 v[96:97], v[6:7], v[128:129], v[54:55]
	v_pk_fma_f32 v[80:81], v[22:23], v[128:129], v[80:81]
	v_pk_fma_f32 v[112:113], v[38:39], v[128:129], v[112:113]
	v_lshlrev_b32_e32 v126, 16, v188
	v_and_b32_e32 v127, 0xffff0000, v188
	v_pk_fma_f32 v[98:99], v[16:17], v[126:127], v[64:65]
	v_pk_fma_f32 v[82:83], v[32:33], v[126:127], v[82:83]
	v_pk_fma_f32 v[114:115], v[48:49], v[126:127], v[114:115]
	v_lshlrev_b32_e32 v128, 16, v189
	v_and_b32_e32 v129, 0xffff0000, v189
	v_pk_fma_f32 v[100:101], v[18:19], v[128:129], v[66:67]
	v_pk_fma_f32 v[84:85], v[34:35], v[128:129], v[84:85]
	v_pk_fma_f32 v[116:117], v[50:51], v[128:129], v[116:117]
	v_lshlrev_b32_e32 v126, 16, v190
	v_and_b32_e32 v127, 0xffff0000, v190
	v_pk_fma_f32 v[102:103], v[12:13], v[126:127], v[60:61]
	v_pk_fma_f32 v[86:87], v[28:29], v[126:127], v[86:87]
	v_pk_fma_f32 v[118:119], v[44:45], v[126:127], v[118:119]
	v_lshlrev_b32_e32 v128, 16, v191
	v_and_b32_e32 v129, 0xffff0000, v191
	v_pk_fma_f32 v[104:105], v[14:15], v[128:129], v[62:63]
	v_pk_fma_f32 v[88:89], v[30:31], v[128:129], v[88:89]
	v_pk_fma_f32 v[120:121], v[46:47], v[128:129], v[120:121]
	global_load_dwordx4 v[184:187], v[72:73], off nt
	v_lshl_add_u64 v[72:73], v[72:73], 0, s[10:11]
	global_load_dwordx4 v[188:191], v[72:73], off nt
	v_lshl_add_u64 v[72:73], v[72:73], 0, s[10:11]
	v_mul_f32_e32 v122, 0xbfb8aa3b, v106
	v_mul_f32_e32 v123, 0xbfb8aa3b, v107
	v_mul_f32_e32 v124, 0xbfb8aa3b, v108
	v_mul_f32_e32 v125, 0xbfb8aa3b, v109
	v_mul_f32_e32 v126, 0xbfb8aa3b, v110
	v_mul_f32_e32 v127, 0xbfb8aa3b, v111
	v_mul_f32_e32 v128, 0xbfb8aa3b, v112
	v_mul_f32_e32 v129, 0xbfb8aa3b, v113
	v_exp_f32_e32 v122, v122
	v_exp_f32_e32 v123, v123
	v_exp_f32_e32 v124, v124
	v_exp_f32_e32 v125, v125
	v_exp_f32_e32 v126, v126
	v_exp_f32_e32 v127, v127
	v_exp_f32_e32 v128, v128
	v_exp_f32_e32 v129, v129
	v_add_f32_e32 v122, 1.0, v122
	v_add_f32_e32 v123, 1.0, v123
	v_add_f32_e32 v124, 1.0, v124
	v_add_f32_e32 v125, 1.0, v125
	v_add_f32_e32 v126, 1.0, v126
	v_add_f32_e32 v127, 1.0, v127
	v_add_f32_e32 v128, 1.0, v128
	v_add_f32_e32 v129, 1.0, v129
	v_rcp_f32_e32 v122, v122
	v_rcp_f32_e32 v123, v123
	v_rcp_f32_e32 v124, v124
	v_rcp_f32_e32 v125, v125
	v_rcp_f32_e32 v126, v126
	v_rcp_f32_e32 v127, v127
	v_rcp_f32_e32 v128, v128
	v_rcp_f32_e32 v129, v129
	v_pk_mul_f32 v[106:107], v[106:107], v[122:123]
	v_pk_mul_f32 v[108:109], v[108:109], v[124:125]
	v_pk_mul_f32 v[110:111], v[110:111], v[126:127]
	v_pk_mul_f32 v[112:113], v[112:113], v[128:129]
	v_pk_mul_f32 v[106:107], v[114:115], v[106:107]
	v_pk_mul_f32 v[108:109], v[116:117], v[108:109]
	v_pk_mul_f32 v[110:111], v[118:119], v[110:111]
	v_pk_mul_f32 v[112:113], v[120:121], v[112:113]
	v_cvt_pk_bf16_f32 v138, v106, v107
	v_cvt_pk_bf16_f32 v139, v108, v109
	v_cvt_pk_bf16_f32 v140, v110, v111
	v_cvt_pk_bf16_f32 v141, v112, v113
	global_store_dwordx4 v[70:71], v[138:141], off
	v_lshl_add_u64 v[70:71], v[70:71], 0, s[10:11]
	s_waitcnt vmcnt(24)
	v_lshlrev_b32_e32 v126, 16, v192
	v_and_b32_e32 v127, 0xffff0000, v192
	v_pk_fma_f32 v[106:107], v[8:9], v[126:127], v[56:57]
	v_pk_fma_f32 v[90:91], v[24:25], v[126:127], v[90:91]
	v_pk_fma_f32 v[74:75], v[40:41], v[126:127], v[74:75]
	v_lshlrev_b32_e32 v128, 16, v193
	v_and_b32_e32 v129, 0xffff0000, v193
	v_pk_fma_f32 v[108:109], v[10:11], v[128:129], v[58:59]
	v_pk_fma_f32 v[92:93], v[26:27], v[128:129], v[92:93]
	v_pk_fma_f32 v[76:77], v[42:43], v[128:129], v[76:77]
	v_lshlrev_b32_e32 v126, 16, v194
	v_and_b32_e32 v127, 0xffff0000, v194
	v_pk_fma_f32 v[110:111], v[4:5], v[126:127], v[52:53]
	v_pk_fma_f32 v[94:95], v[20:21], v[126:127], v[94:95]
	v_pk_fma_f32 v[78:79], v[36:37], v[126:127], v[78:79]
	v_lshlrev_b32_e32 v128, 16, v195
	v_and_b32_e32 v129, 0xffff0000, v195
	v_pk_fma_f32 v[112:113], v[6:7], v[128:129], v[54:55]
	v_pk_fma_f32 v[96:97], v[22:23], v[128:129], v[96:97]
	v_pk_fma_f32 v[80:81], v[38:39], v[128:129], v[80:81]
	v_lshlrev_b32_e32 v126, 16, v196
	v_and_b32_e32 v127, 0xffff0000, v196
	v_pk_fma_f32 v[114:115], v[16:17], v[126:127], v[64:65]
	v_pk_fma_f32 v[98:99], v[32:33], v[126:127], v[98:99]
	v_pk_fma_f32 v[82:83], v[48:49], v[126:127], v[82:83]
	v_lshlrev_b32_e32 v128, 16, v197
	v_and_b32_e32 v129, 0xffff0000, v197
	v_pk_fma_f32 v[116:117], v[18:19], v[128:129], v[66:67]
	v_pk_fma_f32 v[100:101], v[34:35], v[128:129], v[100:101]
	v_pk_fma_f32 v[84:85], v[50:51], v[128:129], v[84:85]
	v_lshlrev_b32_e32 v126, 16, v198
	v_and_b32_e32 v127, 0xffff0000, v198
	v_pk_fma_f32 v[118:119], v[12:13], v[126:127], v[60:61]
	v_pk_fma_f32 v[102:103], v[28:29], v[126:127], v[102:103]
	v_pk_fma_f32 v[86:87], v[44:45], v[126:127], v[86:87]
	v_lshlrev_b32_e32 v128, 16, v199
	v_and_b32_e32 v129, 0xffff0000, v199
	v_pk_fma_f32 v[120:121], v[14:15], v[128:129], v[62:63]
	v_pk_fma_f32 v[104:105], v[30:31], v[128:129], v[104:105]
	v_pk_fma_f32 v[88:89], v[46:47], v[128:129], v[88:89]
; __device__ __forceinline__ uint4 ld_nt16(const void* p) { const u32x4_t t = __builtin_nontemporal_load((const u32x4_t*)p); return make_uint4(t[0], t[1], t[2], t[3]); }
; __device__ __forceinline__ unsigned pk2(float lo, float hi) { f32x2_t v = {lo, hi}; bf16x2_t b = __builtin_convertvector(v, bf16x2_t); return __builtin_bit_cast(unsigned, b); }
; __device__ __forceinline__ float lo_bf(unsigned u) { return __uint_as_float(u << 16); }
; __device__ __forceinline__ float hi_bf(unsigned u) { return __uint_as_float(u & 0xffff0000u); }
; __device__ __forceinline__ float siluf_(float x) { return x * __builtin_amdgcn_rcpf(1.f + __expf(-x)); }
; __device__ void conv_phase(int swave, const Params& p, int layer, int h) {
;     ...
;     for (int i = 0; i < 16; ++i) {
;       uint4 na = zero4, nv = zero4;
;       if (s0 + i + 1 < SEQ) { na = ld_nt16(base + (size_t)(i + 1) * ULD); nv = ld_nt16(base + (size_t)(i + 1) * ULD + FFNH); }
;       const unsigned rp[4] = {pa.x, pa.y, pa.z, pa.w}, rc[4] = {ca.x, ca.y, ca.z, ca.w}, rn[4] = {na.x, na.y, na.z, na.w};
;       const unsigned qp[4] = {pv.x, pv.y, pv.z, pv.w}, qc[4] = {cv.x, cv.y, cv.z, cv.w}, qn[4] = {nv.x, nv.y, nv.z, nv.w};
;       float oa[8], ov[8];
; #pragma unroll
;       for (int e = 0; e < 4; ++e) {
;         oa[2 * e] = ba[2 * e] + lo_bf(rp[e]) * wa[0][2 * e] + lo_bf(rc[e]) * wa[1][2 * e] + lo_bf(rn[e]) * wa[2][2 * e];
;         oa[2 * e + 1] = ba[2 * e + 1] + hi_bf(rp[e]) * wa[0][2 * e + 1] + hi_bf(rc[e]) * wa[1][2 * e + 1] + hi_bf(rn[e]) * wa[2][2 * e + 1];
;         ov[2 * e] = bv[2 * e] + lo_bf(qp[e]) * wv[0][2 * e] + lo_bf(qc[e]) * wv[1][2 * e] + lo_bf(qn[e]) * wv[2][2 * e];
;         ov[2 * e + 1] = bv[2 * e + 1] + hi_bf(qp[e]) * wv[0][2 * e + 1] + hi_bf(qc[e]) * wv[1][2 * e + 1] + hi_bf(qn[e]) * wv[2][2 * e + 1];
;       }
;       uint4 o;
;       o.x = pk2(siluf_(oa[0]) * ov[0], siluf_(oa[1]) * ov[1]); o.y = pk2(siluf_(oa[2]) * ov[2], siluf_(oa[3]) * ov[3]);
;       o.z = pk2(siluf_(oa[4]) * ov[4], siluf_(oa[5]) * ov[5]); o.w = pk2(siluf_(oa[6]) * ov[6], siluf_(oa[7]) * ov[7]);
;       *(uint4*)(ACT + (size_t)(t0 + i) * FFNH + f8) = o;
	global_load_dwordx4 v[192:195], v[72:73], off nt
	v_lshl_add_u64 v[72:73], v[72:73], 0, s[10:11]
	global_load_dwordx4 v[196:199], v[72:73], off nt
	v_lshl_add_u64 v[72:73], v[72:73], 0, s[10:11]
	v_mul_f32_e32 v122, 0xbfb8aa3b, v74
	v_mul_f32_e32 v123, 0xbfb8aa3b, v75
	v_mul_f32_e32 v124, 0xbfb8aa3b, v76
	v_mul_f32_e32 v125, 0xbfb8aa3b, v77
	v_mul_f32_e32 v126, 0xbfb8aa3b, v78
	v_mul_f32_e32 v127, 0xbfb8aa3b, v79
	v_mul_f32_e32 v128, 0xbfb8aa3b, v80
	v_mul_f32_e32 v129, 0xbfb8aa3b, v81
	v_exp_f32_e32 v122, v122
	v_exp_f32_e32 v123, v123
	v_exp_f32_e32 v124, v124
	v_exp_f32_e32 v125, v125
	v_exp_f32_e32 v126, v126
	v_exp_f32_e32 v127, v127
	v_exp_f32_e32 v128, v128
	v_exp_f32_e32 v129, v129
	v_add_f32_e32 v122, 1.0, v122
	v_add_f32_e32 v123, 1.0, v123
	v_add_f32_e32 v124, 1.0, v124
	v_add_f32_e32 v125, 1.0, v125
	v_add_f32_e32 v126, 1.0, v126
	v_add_f32_e32 v127, 1.0, v127
	v_add_f32_e32 v128, 1.0, v128
	v_add_f32_e32 v129, 1.0, v129
	v_rcp_f32_e32 v122, v122
	v_rcp_f32_e32 v123, v123
	v_rcp_f32_e32 v124, v124
	v_rcp_f32_e32 v125, v125
	v_rcp_f32_e32 v126, v126
	v_rcp_f32_e32 v127, v127
	v_rcp_f32_e32 v128, v128
	v_rcp_f32_e32 v129, v129
	v_pk_mul_f32 v[74:75], v[74:75], v[122:123]
	v_pk_mul_f32 v[76:77], v[76:77], v[124:125]
	v_pk_mul_f32 v[78:79], v[78:79], v[126:127]
	v_pk_mul_f32 v[80:81], v[80:81], v[128:129]
	v_pk_mul_f32 v[74:75], v[82:83], v[74:75]
	v_pk_mul_f32 v[76:77], v[84:85], v[76:77]
	v_pk_mul_f32 v[78:79], v[86:87], v[78:79]
	v_pk_mul_f32 v[80:81], v[88:89], v[80:81]
	v_cvt_pk_bf16_f32 v138, v74, v75
	v_cvt_pk_bf16_f32 v139, v76, v77
	v_cvt_pk_bf16_f32 v140, v78, v79
	v_cvt_pk_bf16_f32 v141, v80, v81
	global_store_dwordx4 v[70:71], v[138:141], off
	v_lshl_add_u64 v[70:71], v[70:71], 0, s[10:11]
	s_waitcnt vmcnt(24)
	v_lshlrev_b32_e32 v126, 16, v200
	v_and_b32_e32 v127, 0xffff0000, v200
	v_pk_fma_f32 v[74:75], v[8:9], v[126:127], v[56:57]
	v_pk_fma_f32 v[106:107], v[24:25], v[126:127], v[106:107]
	v_pk_fma_f32 v[90:91], v[40:41], v[126:127], v[90:91]
	v_lshlrev_b32_e32 v128, 16, v201
	v_and_b32_e32 v129, 0xffff0000, v201
	v_pk_fma_f32 v[76:77], v[10:11], v[128:129], v[58:59]
	v_pk_fma_f32 v[108:109], v[26:27], v[128:129], v[108:109]
	v_pk_fma_f32 v[92:93], v[42:43], v[128:129], v[92:93]
	v_lshlrev_b32_e32 v126, 16, v202
	v_and_b32_e32 v127, 0xffff0000, v202
	v_pk_fma_f32 v[78:79], v[4:5], v[126:127], v[52:53]
	v_pk_fma_f32 v[110:111], v[20:21], v[126:127], v[110:111]
	v_pk_fma_f32 v[94:95], v[36:37], v[126:127], v[94:95]
	v_lshlrev_b32_e32 v128, 16, v203
	v_and_b32_e32 v129, 0xffff0000, v203
	v_pk_fma_f32 v[80:81], v[6:7], v[128:129], v[54:55]
	v_pk_fma_f32 v[112:113], v[22:23], v[128:129], v[112:113]
	v_pk_fma_f32 v[96:97], v[38:39], v[128:129], v[96:97]
	v_lshlrev_b32_e32 v126, 16, v204
	v_and_b32_e32 v127, 0xffff0000, v204
	v_pk_fma_f32 v[82:83], v[16:17], v[126:127], v[64:65]
	v_pk_fma_f32 v[114:115], v[32:33], v[126:127], v[114:115]
	v_pk_fma_f32 v[98:99], v[48:49], v[126:127], v[98:99]
	v_lshlrev_b32_e32 v128, 16, v205
	v_and_b32_e32 v129, 0xffff0000, v205
	v_pk_fma_f32 v[84:85], v[18:19], v[128:129], v[66:67]
	v_pk_fma_f32 v[116:117], v[34:35], v[128:129], v[116:117]
	v_pk_fma_f32 v[100:101], v[50:51], v[128:129], v[100:101]
	v_lshlrev_b32_e32 v126, 16, v206
	v_and_b32_e32 v127, 0xffff0000, v206
	v_pk_fma_f32 v[86:87], v[12:13], v[126:127], v[60:61]
	v_pk_fma_f32 v[118:119], v[28:29], v[126:127], v[118:119]
	v_pk_fma_f32 v[102:103], v[44:45], v[126:127], v[102:103]
	v_lshlrev_b32_e32 v128, 16, v207
	v_and_b32_e32 v129, 0xffff0000, v207
	v_pk_fma_f32 v[88:89], v[14:15], v[128:129], v[62:63]
	v_pk_fma_f32 v[120:121], v[30:31], v[128:129], v[120:121]
	v_pk_fma_f32 v[104:105], v[46:47], v[128:129], v[104:105]
	global_load_dwordx4 v[200:203], v[72:73], off nt
	v_lshl_add_u64 v[72:73], v[72:73], 0, s[10:11]
	global_load_dwordx4 v[204:207], v[72:73], off nt
	v_lshl_add_u64 v[72:73], v[72:73], 0, s[10:11]
	v_mul_f32_e32 v122, 0xbfb8aa3b, v90
	v_mul_f32_e32 v123, 0xbfb8aa3b, v91
	v_mul_f32_e32 v124, 0xbfb8aa3b, v92
	v_mul_f32_e32 v125, 0xbfb8aa3b, v93
	v_mul_f32_e32 v126, 0xbfb8aa3b, v94
	v_mul_f32_e32 v127, 0xbfb8aa3b, v95
	v_mul_f32_e32 v128, 0xbfb8aa3b, v96
	v_mul_f32_e32 v129, 0xbfb8aa3b, v97
	v_exp_f32_e32 v122, v122
	v_exp_f32_e32 v123, v123
	v_exp_f32_e32 v124, v124
	v_exp_f32_e32 v125, v125
	v_exp_f32_e32 v126, v126
	v_exp_f32_e32 v127, v127
	v_exp_f32_e32 v128, v128
	v_exp_f32_e32 v129, v129
	v_add_f32_e32 v122, 1.0, v122
	v_add_f32_e32 v123, 1.0, v123
	v_add_f32_e32 v124, 1.0, v124
	v_add_f32_e32 v125, 1.0, v125
	v_add_f32_e32 v126, 1.0, v126
	v_add_f32_e32 v127, 1.0, v127
	v_add_f32_e32 v128, 1.0, v128
	v_add_f32_e32 v129, 1.0, v129
	v_rcp_f32_e32 v122, v122
	v_rcp_f32_e32 v123, v123
	v_rcp_f32_e32 v124, v124
	v_rcp_f32_e32 v125, v125
	v_rcp_f32_e32 v126, v126
	v_rcp_f32_e32 v127, v127
	v_rcp_f32_e32 v128, v128
	v_rcp_f32_e32 v129, v129
	v_pk_mul_f32 v[90:91], v[90:91], v[122:123]
	v_pk_mul_f32 v[92:93], v[92:93], v[124:125]
	v_pk_mul_f32 v[94:95], v[94:95], v[126:127]
	v_pk_mul_f32 v[96:97], v[96:97], v[128:129]
	v_pk_mul_f32 v[90:91], v[98:99], v[90:91]
	v_pk_mul_f32 v[92:93], v[100:101], v[92:93]
	v_pk_mul_f32 v[94:95], v[102:103], v[94:95]
	v_pk_mul_f32 v[96:97], v[104:105], v[96:97]
	v_cvt_pk_bf16_f32 v138, v90, v91
	v_cvt_pk_bf16_f32 v139, v92, v93
	v_cvt_pk_bf16_f32 v140, v94, v95
	v_cvt_pk_bf16_f32 v141, v96, v97
	global_store_dwordx4 v[70:71], v[138:141], off
	v_lshl_add_u64 v[70:71], v[70:71], 0, s[10:11]
	s_waitcnt vmcnt(24)
; __device__ __forceinline__ uint4 ld_nt16(const void* p) { const u32x4_t t = __builtin_nontemporal_load((const u32x4_t*)p); return make_uint4(t[0], t[1], t[2], t[3]); }
; __device__ __forceinline__ unsigned pk2(float lo, float hi) { f32x2_t v = {lo, hi}; bf16x2_t b = __builtin_convertvector(v, bf16x2_t); return __builtin_bit_cast(unsigned, b); }
; __device__ __forceinline__ float lo_bf(unsigned u) { return __uint_as_float(u << 16); }
; __device__ __forceinline__ float hi_bf(unsigned u) { return __uint_as_float(u & 0xffff0000u); }
; __device__ __forceinline__ float siluf_(float x) { return x * __builtin_amdgcn_rcpf(1.f + __expf(-x)); }
; __device__ void conv_phase(int swave, const Params& p, int layer, int h) {
;     ...
;     for (int i = 0; i < 16; ++i) {
;       uint4 na = zero4, nv = zero4;
;       if (s0 + i + 1 < SEQ) { na = ld_nt16(base + (size_t)(i + 1) * ULD); nv = ld_nt16(base + (size_t)(i + 1) * ULD + FFNH); }
;       const unsigned rp[4] = {pa.x, pa.y, pa.z, pa.w}, rc[4] = {ca.x, ca.y, ca.z, ca.w}, rn[4] = {na.x, na.y, na.z, na.w};
;       const unsigned qp[4] = {pv.x, pv.y, pv.z, pv.w}, qc[4] = {cv.x, cv.y, cv.z, cv.w}, qn[4] = {nv.x, nv.y, nv.z, nv.w};
;       float oa[8], ov[8];
; #pragma unroll
;       for (int e = 0; e < 4; ++e) {
;         oa[2 * e] = ba[2 * e] + lo_bf(rp[e]) * wa[0][2 * e] + lo_bf(rc[e]) * wa[1][2 * e] + lo_bf(rn[e]) * wa[2][2 * e];
;         oa[2 * e + 1] = ba[2 * e + 1] + hi_bf(rp[e]) * wa[0][2 * e + 1] + hi_bf(rc[e]) * wa[1][2 * e + 1] + hi_bf(rn[e]) * wa[2][2 * e + 1];
;         ov[2 * e] = bv[2 * e] + lo_bf(qp[e]) * wv[0][2 * e] + lo_bf(qc[e]) * wv[1][2 * e] + lo_bf(qn[e]) * wv[2][2 * e];
;         ov[2 * e + 1] = bv[2 * e + 1] + hi_bf(qp[e]) * wv[0][2 * e + 1] + hi_bf(qc[e]) * wv[1][2 * e + 1] + hi_bf(qn[e]) * wv[2][2 * e + 1];
;       }
;       uint4 o;
;       o.x = pk2(siluf_(oa[0]) * ov[0], siluf_(oa[1]) * ov[1]); o.y = pk2(siluf_(oa[2]) * ov[2], siluf_(oa[3]) * ov[3]);
;       o.z = pk2(siluf_(oa[4]) * ov[4], siluf_(oa[5]) * ov[5]); o.w = pk2(siluf_(oa[6]) * ov[6], siluf_(oa[7]) * ov[7]);
;       *(uint4*)(ACT + (size_t)(t0 + i) * FFNH + f8) = o;
;       pa = ca; pv = cv; ca = na; cv = nv;
;     }
;   }
	v_lshlrev_b32_e32 v126, 16, v208
	v_and_b32_e32 v127, 0xffff0000, v208
	v_pk_fma_f32 v[74:75], v[24:25], v[126:127], v[74:75]
	v_pk_fma_f32 v[106:107], v[40:41], v[126:127], v[106:107]
	v_lshlrev_b32_e32 v128, 16, v209
	v_and_b32_e32 v129, 0xffff0000, v209
	v_pk_fma_f32 v[76:77], v[26:27], v[128:129], v[76:77]
	v_pk_fma_f32 v[108:109], v[42:43], v[128:129], v[108:109]
	v_lshlrev_b32_e32 v126, 16, v210
	v_and_b32_e32 v127, 0xffff0000, v210
	v_pk_fma_f32 v[78:79], v[20:21], v[126:127], v[78:79]
	v_pk_fma_f32 v[110:111], v[36:37], v[126:127], v[110:111]
	v_lshlrev_b32_e32 v128, 16, v211
	v_and_b32_e32 v129, 0xffff0000, v211
	v_pk_fma_f32 v[80:81], v[22:23], v[128:129], v[80:81]
	v_pk_fma_f32 v[112:113], v[38:39], v[128:129], v[112:113]
	v_lshlrev_b32_e32 v126, 16, v212
	v_and_b32_e32 v127, 0xffff0000, v212
	v_pk_fma_f32 v[82:83], v[32:33], v[126:127], v[82:83]
	v_pk_fma_f32 v[114:115], v[48:49], v[126:127], v[114:115]
	v_lshlrev_b32_e32 v128, 16, v213
	v_and_b32_e32 v129, 0xffff0000, v213
	v_pk_fma_f32 v[84:85], v[34:35], v[128:129], v[84:85]
	v_pk_fma_f32 v[116:117], v[50:51], v[128:129], v[116:117]
	v_lshlrev_b32_e32 v126, 16, v214
	v_and_b32_e32 v127, 0xffff0000, v214
	v_pk_fma_f32 v[86:87], v[28:29], v[126:127], v[86:87]
	v_pk_fma_f32 v[118:119], v[44:45], v[126:127], v[118:119]
	v_lshlrev_b32_e32 v128, 16, v215
	v_and_b32_e32 v129, 0xffff0000, v215
	v_pk_fma_f32 v[88:89], v[30:31], v[128:129], v[88:89]
	v_pk_fma_f32 v[120:121], v[46:47], v[128:129], v[120:121]
	global_load_dwordx4 v[208:211], v[72:73], off nt
	v_lshl_add_u64 v[72:73], v[72:73], 0, s[10:11]
	global_load_dwordx4 v[212:215], v[72:73], off nt
	v_lshl_add_u64 v[72:73], v[72:73], 0, s[10:11]
	v_mul_f32_e32 v122, 0xbfb8aa3b, v106
	v_mul_f32_e32 v123, 0xbfb8aa3b, v107
	v_mul_f32_e32 v124, 0xbfb8aa3b, v108
	v_mul_f32_e32 v125, 0xbfb8aa3b, v109
	v_mul_f32_e32 v126, 0xbfb8aa3b, v110
	v_mul_f32_e32 v127, 0xbfb8aa3b, v111
	v_mul_f32_e32 v128, 0xbfb8aa3b, v112
	v_mul_f32_e32 v129, 0xbfb8aa3b, v113
	v_exp_f32_e32 v122, v122
	v_exp_f32_e32 v123, v123
	v_exp_f32_e32 v124, v124
	v_exp_f32_e32 v125, v125
	v_exp_f32_e32 v126, v126
	v_exp_f32_e32 v127, v127
	v_exp_f32_e32 v128, v128
	v_exp_f32_e32 v129, v129
	v_add_f32_e32 v122, 1.0, v122
	v_add_f32_e32 v123, 1.0, v123
	v_add_f32_e32 v124, 1.0, v124
	v_add_f32_e32 v125, 1.0, v125
	v_add_f32_e32 v126, 1.0, v126
	v_add_f32_e32 v127, 1.0, v127
	v_add_f32_e32 v128, 1.0, v128
	v_add_f32_e32 v129, 1.0, v129
	v_rcp_f32_e32 v122, v122
	v_rcp_f32_e32 v123, v123
	v_rcp_f32_e32 v124, v124
	v_rcp_f32_e32 v125, v125
	v_rcp_f32_e32 v126, v126
	v_rcp_f32_e32 v127, v127
	v_rcp_f32_e32 v128, v128
	v_rcp_f32_e32 v129, v129
	v_pk_mul_f32 v[106:107], v[106:107], v[122:123]
	v_pk_mul_f32 v[108:109], v[108:109], v[124:125]
	v_pk_mul_f32 v[110:111], v[110:111], v[126:127]
	v_pk_mul_f32 v[112:113], v[112:113], v[128:129]
	v_pk_mul_f32 v[106:107], v[114:115], v[106:107]
	v_pk_mul_f32 v[108:109], v[116:117], v[108:109]
	v_pk_mul_f32 v[110:111], v[118:119], v[110:111]
	v_pk_mul_f32 v[112:113], v[120:121], v[112:113]
	v_cvt_pk_bf16_f32 v138, v106, v107
	v_cvt_pk_bf16_f32 v139, v108, v109
	v_cvt_pk_bf16_f32 v140, v110, v111
	v_cvt_pk_bf16_f32 v141, v112, v113
	global_store_dwordx4 v[70:71], v[138:141], off
	v_lshl_add_u64 v[70:71], v[70:71], 0, s[10:11]
	s_waitcnt vmcnt(24)
	v_cndmask_b32_e64 v216, 0, v216, s[20:21]
	v_cndmask_b32_e64 v217, 0, v217, s[20:21]
	v_cndmask_b32_e64 v218, 0, v218, s[20:21]
	v_cndmask_b32_e64 v219, 0, v219, s[20:21]
	v_cndmask_b32_e64 v220, 0, v220, s[20:21]
	v_cndmask_b32_e64 v221, 0, v221, s[20:21]
	v_cndmask_b32_e64 v222, 0, v222, s[20:21]
	v_cndmask_b32_e64 v223, 0, v223, s[20:21]
	v_lshlrev_b32_e32 v126, 16, v216
	v_and_b32_e32 v127, 0xffff0000, v216
	v_pk_fma_f32 v[74:75], v[40:41], v[126:127], v[74:75]
	v_lshlrev_b32_e32 v128, 16, v217
	v_and_b32_e32 v129, 0xffff0000, v217
	v_pk_fma_f32 v[76:77], v[42:43], v[128:129], v[76:77]
	v_lshlrev_b32_e32 v126, 16, v218
	v_and_b32_e32 v127, 0xffff0000, v218
	v_pk_fma_f32 v[78:79], v[36:37], v[126:127], v[78:79]
	v_lshlrev_b32_e32 v128, 16, v219
	v_and_b32_e32 v129, 0xffff0000, v219
	v_pk_fma_f32 v[80:81], v[38:39], v[128:129], v[80:81]
	v_lshlrev_b32_e32 v126, 16, v220
	v_and_b32_e32 v127, 0xffff0000, v220
	v_pk_fma_f32 v[82:83], v[48:49], v[126:127], v[82:83]
	v_lshlrev_b32_e32 v128, 16, v221
	v_and_b32_e32 v129, 0xffff0000, v221
	v_pk_fma_f32 v[84:85], v[50:51], v[128:129], v[84:85]
	v_lshlrev_b32_e32 v126, 16, v222
	v_and_b32_e32 v127, 0xffff0000, v222
	v_pk_fma_f32 v[86:87], v[44:45], v[126:127], v[86:87]
	v_lshlrev_b32_e32 v128, 16, v223
	v_and_b32_e32 v129, 0xffff0000, v223
	v_pk_fma_f32 v[88:89], v[46:47], v[128:129], v[88:89]
	global_load_dwordx4 v[216:219], v[72:73], off nt
	v_lshl_add_u64 v[72:73], v[72:73], 0, s[10:11]
	global_load_dwordx4 v[220:223], v[72:73], off nt
	v_lshl_add_u64 v[72:73], v[72:73], 0, s[10:11]
	global_load_dwordx4 v[224:227], v[72:73], off nt
	v_lshl_add_u64 v[72:73], v[72:73], 0, s[10:11]
	global_load_dwordx4 v[228:231], v[72:73], off nt
	v_lshl_add_u64 v[72:73], v[72:73], 0, s[10:11]
	global_load_dwordx4 v[232:235], v[72:73], off nt
	v_lshl_add_u64 v[72:73], v[72:73], 0, s[10:11]
	global_load_dwordx4 v[236:239], v[72:73], off nt
	v_lshl_add_u64 v[72:73], v[72:73], 0, s[10:11]
	v_mul_f32_e32 v122, 0xbfb8aa3b, v74
	v_mul_f32_e32 v123, 0xbfb8aa3b, v75
	v_mul_f32_e32 v124, 0xbfb8aa3b, v76
	v_mul_f32_e32 v125, 0xbfb8aa3b, v77
	v_mul_f32_e32 v126, 0xbfb8aa3b, v78
	v_mul_f32_e32 v127, 0xbfb8aa3b, v79
	v_mul_f32_e32 v128, 0xbfb8aa3b, v80
	v_mul_f32_e32 v129, 0xbfb8aa3b, v81
	v_exp_f32_e32 v122, v122
	v_exp_f32_e32 v123, v123
	v_exp_f32_e32 v124, v124
	v_exp_f32_e32 v125, v125
	v_exp_f32_e32 v126, v126
	v_exp_f32_e32 v127, v127
	v_exp_f32_e32 v128, v128
	v_exp_f32_e32 v129, v129
	v_add_f32_e32 v122, 1.0, v122
	v_add_f32_e32 v123, 1.0, v123
	v_add_f32_e32 v124, 1.0, v124
	v_add_f32_e32 v125, 1.0, v125
	v_add_f32_e32 v126, 1.0, v126
	v_add_f32_e32 v127, 1.0, v127
	v_add_f32_e32 v128, 1.0, v128
	v_add_f32_e32 v129, 1.0, v129
	v_rcp_f32_e32 v122, v122
	v_rcp_f32_e32 v123, v123
	v_rcp_f32_e32 v124, v124
	v_rcp_f32_e32 v125, v125
	v_rcp_f32_e32 v126, v126
	v_rcp_f32_e32 v127, v127
	v_rcp_f32_e32 v128, v128
	v_rcp_f32_e32 v129, v129
	v_pk_mul_f32 v[74:75], v[74:75], v[122:123]
	v_pk_mul_f32 v[76:77], v[76:77], v[124:125]
	v_pk_mul_f32 v[78:79], v[78:79], v[126:127]
	v_pk_mul_f32 v[80:81], v[80:81], v[128:129]
	v_pk_mul_f32 v[74:75], v[82:83], v[74:75]
	v_pk_mul_f32 v[76:77], v[84:85], v[76:77]
	v_pk_mul_f32 v[78:79], v[86:87], v[78:79]
	v_pk_mul_f32 v[80:81], v[88:89], v[80:81]
	v_cvt_pk_bf16_f32 v138, v74, v75
	v_cvt_pk_bf16_f32 v139, v76, v77
	v_cvt_pk_bf16_f32 v140, v78, v79
	v_cvt_pk_bf16_f32 v141, v80, v81
	global_store_dwordx4 v[70:71], v[138:141], off
	v_lshl_add_u64 v[70:71], v[70:71], 0, s[10:11]
	s_branch .LBB0_707
